# speedup vs baseline: 1.0379x; 1.0120x over previous
; template <int EPI, int PN>
; __device__ void gemm_phase(const Params& p, const u16* __restrict__ A, const u16* __restrict__ Bt, int nNt, char* smem) {
;     ...
;     for (int kt = 0; kt < 32; ++kt) {
;       asm volatile("s_waitcnt vmcnt(0)" ::: "memory");
;       __builtin_amdgcn_s_barrier();
;       const u16* Ab = ring + (kt & 1) * STG;
;       const u16* Bb = Ab + 16384;
;       u16* st = ring + ((kt + 1) & 1) * STG;
;       const bool pre = (kt + 1 < 32);
;       s16x8 af[2][4], bf[2][2];
;       auto ldfrag = [&](int ks, int slot) {
; #pragma unroll
;         for (int i = 0; i < 4; ++i) {
;           const int row = wr * 128 + i * 32 + lr;
;           af[slot][i] = *(const s16x8*)(Ab + row * 64 + (((ks * 2 + lh) ^ ((row >> 1) & 7)) * 8));
;         }
; #pragma unroll
;         for (int j = 0; j < 2; ++j) {
;           const int rowb = nh * 128 + wc * 64 + j * 32 + lr;
;           bf[slot][j] = *(const s16x8*)(Bb + rowb * 64 + (((ks * 2 + lh) ^ ((rowb >> 1) & 7)) * 8));
;         }
;       };
;       ldfrag(0, 0);
;       ldfrag(1, 1);
;       __builtin_amdgcn_sched_barrier(0);
; #pragma unroll
;       for (int ks = 0; ks < 4; ++ks) {
;         const int slot = ks & 1;
; #pragma unroll
;         for (int i = 0; i < 4; ++i) {
;           acc[i][0] = mfma32(af[slot][i], bf[slot][0], acc[i][0]);
;           acc[i][1] = mfma32(af[slot][i], bf[slot][1], acc[i][1]);
;           __builtin_amdgcn_sched_barrier(0);
;           if (pre && (i & 1) == 0) {
;             const int pi = ks * 2 + (i >> 1);
;             if (pi < 4) glds16(Ag0 + (size_t)pi * 64 * LDK + (kt + 1) * 64, st + (srow + 64 * pi) * 64 + sch * 8);
;             else glds16(Bg0 + (size_t)(pi - 4) * 64 * LDK + (kt + 1) * 64, st + 16384 + (srow + 64 * (pi - 4)) * 64 + sch * 8);
;             __builtin_amdgcn_sched_barrier(0);
;           }
;         }
;         if (ks + 2 < 4) { ldfrag(ks + 2, slot); __builtin_amdgcn_sched_barrier(0); }
;       }
.Lrot129_loop:
	s_add_i32 s13, s12, 0xffff8000
	s_and_b32 s13, s13, 0x8000
	s_lshl_b32 s13, s13, 1
	v_lshl_or_b32 v128, v143, 1, s13
	v_lshl_add_u32 v149, v147, 1, s13
	s_and_b32 s98, s12, 0x8000
	s_lshl_b32 s98, s98, 1
	s_waitcnt lgkmcnt(7)
	v_mfma_f32_32x32x16_bf16 v[64:79], v[178:181], v[194:197], v[64:79]
	v_add3_u32 v226, s98, v162, v156
	s_waitcnt lgkmcnt(6)
	v_mfma_f32_32x32x16_bf16 v[112:127], v[178:181], v[198:201], v[112:127]
	v_readfirstlane_b32 s100, v226
	s_mov_b32 s20, m0
	s_add_i32 m0, s100, 0x8000
	s_nop 0
	global_load_lds_dwordx4 v[160:161], off
	v_mfma_f32_32x32x16_bf16 v[32:47], v[182:185], v[194:197], v[32:47]
	v_lshl_add_u64 v[178:179], v[160:161], 0, s[2:3]
	s_add_i32 m0, s100, 0xa000
	s_nop 0
	global_load_lds_dwordx4 v[178:179], off
	v_mfma_f32_32x32x16_bf16 v[96:111], v[182:185], v[198:201], v[96:111]
	v_lshl_add_u64 v[180:181], v[160:161], 0, s[4:5]
	s_add_i32 m0, s100, 0xc000
	s_nop 0
	global_load_lds_dwordx4 v[180:181], off
	v_mfma_f32_32x32x16_bf16 v[16:31], v[186:189], v[194:197], v[16:31]
	v_lshl_add_u64 v[178:179], v[160:161], 0, s[6:7]
	s_add_i32 m0, s100, 0xe000
	s_nop 0
	global_load_lds_dwordx4 v[178:179], off
	s_mov_b32 m0, s20
	v_mfma_f32_32x32x16_bf16 v[80:95], v[186:189], v[198:201], v[80:95]
	v_mfma_f32_32x32x16_bf16 v[0:15], v[190:193], v[194:197], v[0:15]
	v_mfma_f32_32x32x16_bf16 v[48:63], v[190:193], v[198:201], v[48:63]
	v_lshl_add_u64 v[160:161], v[160:161], 0, s[8:9]
	v_add_u32_e32 v177, v128, v175
	ds_read_b128 v[178:181], v177
	ds_read_b128 v[182:185], v177 offset:4096
	ds_read_b128 v[186:189], v177 offset:8192
	ds_read_b128 v[190:193], v177 offset:12288
	v_add_u32_e32 v177, v149, v175
	ds_read_b128 v[194:197], v177 offset:32768
	ds_read_b128 v[198:201], v177 offset:36864
	s_waitcnt lgkmcnt(7)
	v_mfma_f32_32x32x16_bf16 v[64:79], v[202:205], v[218:221], v[64:79]
	s_waitcnt lgkmcnt(6)
	v_mfma_f32_32x32x16_bf16 v[112:127], v[202:205], v[222:225], v[112:127]
	v_mfma_f32_32x32x16_bf16 v[32:47], v[206:209], v[218:221], v[32:47]
	v_mfma_f32_32x32x16_bf16 v[96:111], v[206:209], v[222:225], v[96:111]
	v_mfma_f32_32x32x16_bf16 v[16:31], v[210:213], v[218:221], v[16:31]
	v_mfma_f32_32x32x16_bf16 v[80:95], v[210:213], v[222:225], v[80:95]
	v_mfma_f32_32x32x16_bf16 v[0:15], v[214:217], v[218:221], v[0:15]
	v_mfma_f32_32x32x16_bf16 v[48:63], v[214:217], v[222:225], v[48:63]
	v_add_u32_e32 v128, v128, v176
	ds_read_b128 v[202:205], v128
	ds_read_b128 v[206:209], v128 offset:4096
	ds_read_b128 v[210:213], v128 offset:8192
	ds_read_b128 v[214:217], v128 offset:12288
	v_add_u32_e32 v128, v149, v176
	ds_read_b128 v[218:221], v128 offset:32768
	ds_read_b128 v[222:225], v128 offset:36864
	s_waitcnt lgkmcnt(7)
	v_mfma_f32_32x32x16_bf16 v[64:79], v[178:181], v[194:197], v[64:79]
	s_waitcnt lgkmcnt(6)
	v_mfma_f32_32x32x16_bf16 v[112:127], v[178:181], v[198:201], v[112:127]
	v_mfma_f32_32x32x16_bf16 v[32:47], v[182:185], v[194:197], v[32:47]
	v_mfma_f32_32x32x16_bf16 v[96:111], v[182:185], v[198:201], v[96:111]
	v_mfma_f32_32x32x16_bf16 v[16:31], v[186:189], v[194:197], v[16:31]
	v_mfma_f32_32x32x16_bf16 v[80:95], v[186:189], v[198:201], v[80:95]
	v_mfma_f32_32x32x16_bf16 v[0:15], v[190:193], v[194:197], v[0:15]
	v_mfma_f32_32x32x16_bf16 v[48:63], v[190:193], v[198:201], v[48:63]
	v_lshl_or_b32 v227, v143, 1, s98
	v_lshl_add_u32 v229, v147, 1, s98
	v_add_u32_e32 v228, v227, v173
	v_add_u32_e32 v230, v229, v173
	s_waitcnt vmcnt(0) lgkmcnt(0)
	s_barrier
	ds_read_b128 v[178:181], v228
	ds_read_b128 v[182:185], v228 offset:4096
	ds_read_b128 v[186:189], v228 offset:8192
	ds_read_b128 v[190:193], v228 offset:12288
	ds_read_b128 v[194:197], v230 offset:32768
	ds_read_b128 v[198:201], v230 offset:36864
	v_add3_u32 v226, s13, v162, v156
	v_mfma_f32_32x32x16_bf16 v[64:79], v[202:205], v[218:221], v[64:79]
	v_readfirstlane_b32 s99, v226
	s_mov_b32 s20, m0
	s_mov_b32 m0, s99
	s_nop 0
	global_load_lds_dwordx4 v[158:159], off
	v_mfma_f32_32x32x16_bf16 v[112:127], v[202:205], v[222:225], v[112:127]
	v_lshl_add_u64 v[232:233], v[158:159], 0, s[2:3]
	s_add_i32 m0, s99, 0x2000
	s_nop 0
	global_load_lds_dwordx4 v[232:233], off
	v_mfma_f32_32x32x16_bf16 v[32:47], v[206:209], v[218:221], v[32:47]
	v_lshl_add_u64 v[234:235], v[158:159], 0, s[4:5]
	s_add_i32 m0, s99, 0x4000
	s_nop 0
	global_load_lds_dwordx4 v[234:235], off
	v_mfma_f32_32x32x16_bf16 v[96:111], v[206:209], v[222:225], v[96:111]
	v_lshl_add_u64 v[232:233], v[158:159], 0, s[6:7]
	s_add_i32 m0, s99, 0x6000
	s_nop 0
	global_load_lds_dwordx4 v[232:233], off
	s_mov_b32 m0, s20
	v_mfma_f32_32x32x16_bf16 v[16:31], v[210:213], v[218:221], v[16:31]
	v_mfma_f32_32x32x16_bf16 v[80:95], v[210:213], v[222:225], v[80:95]
	v_mfma_f32_32x32x16_bf16 v[0:15], v[214:217], v[218:221], v[0:15]
	v_mfma_f32_32x32x16_bf16 v[48:63], v[214:217], v[222:225], v[48:63]
	v_add_u32_e32 v228, v227, v174
	v_add_u32_e32 v230, v229, v174
	ds_read_b128 v[202:205], v228
	ds_read_b128 v[206:209], v228 offset:4096
	ds_read_b128 v[210:213], v228 offset:8192
	ds_read_b128 v[214:217], v228 offset:12288
	ds_read_b128 v[218:221], v230 offset:32768
	ds_read_b128 v[222:225], v230 offset:36864
	s_add_i32 s12, s12, 0x8000
	v_lshl_add_u64 v[158:159], v[158:159], 0, s[8:9]
	s_cmp_eq_u32 s12, 0xf8000
	s_cbranch_scc0 .Lrot129_loop
; template <int EPI, int PN>
; __device__ void gemm_phase(const Params& p, const u16* __restrict__ A, const u16* __restrict__ Bt, int nNt, char* smem) {
;     ...
;   for (int q = jb;; q += NJ) {
;     const int pl = q / (4 * PN), w = q % (4 * PN);
;     const int gp = pl * 8 + xcd;
;     if (gp >= npatch) break;
;     const int mt = (gp / npn) * 4 + (w & 3), nt = (gp % npn) * PN + (w >> 2);
;     const int gch = sch ^ ((srow >> 1) & 7);
;     const u16* Ag0 = A + (size_t)(mt * 256 + srow) * LDK + gch * 8;
;     const u16* Bg0 = Bt + (size_t)(nt * 256 + srow) * LDK + gch * 8;
;     ...
;     for (int kt = 0; kt < 32; ++kt) {
;       asm volatile("s_waitcnt vmcnt(0)" ::: "memory");
;       __builtin_amdgcn_s_barrier();
;       const u16* Ab = ring + (kt & 1) * STG;
;       const u16* Bb = Ab + 16384;
;       u16* st = ring + ((kt + 1) & 1) * STG;
;       const bool pre = (kt + 1 < 32);
;       s16x8 af[2][4], bf[2][2];
;       auto ldfrag = [&](int ks, int slot) {
; #pragma unroll
;         for (int i = 0; i < 4; ++i) {
;           const int row = wr * 128 + i * 32 + lr;
;           af[slot][i] = *(const s16x8*)(Ab + row * 64 + (((ks * 2 + lh) ^ ((row >> 1) & 7)) * 8));
;         }
; #pragma unroll
;         for (int j = 0; j < 2; ++j) {
;           const int rowb = nh * 128 + wc * 64 + j * 32 + lr;
;           bf[slot][j] = *(const s16x8*)(Bb + rowb * 64 + (((ks * 2 + lh) ^ ((rowb >> 1) & 7)) * 8));
;         }
;       };
;       ldfrag(0, 0);
;       ldfrag(1, 1);
;       __builtin_amdgcn_sched_barrier(0);
; #pragma unroll
;       for (int ks = 0; ks < 4; ++ks) {
;         const int slot = ks & 1;
; #pragma unroll
;         for (int i = 0; i < 4; ++i) {
;           acc[i][0] = mfma32(af[slot][i], bf[slot][0], acc[i][0]);
;           acc[i][1] = mfma32(af[slot][i], bf[slot][1], acc[i][1]);
;           __builtin_amdgcn_sched_barrier(0);
;           if (pre && (i & 1) == 0) {
;             const int pi = ks * 2 + (i >> 1);
;             if (pi < 4) glds16(Ag0 + (size_t)pi * 64 * LDK + (kt + 1) * 64, st + (srow + 64 * pi) * 64 + sch * 8);
;             else glds16(Bg0 + (size_t)(pi - 4) * 64 * LDK + (kt + 1) * 64, st + 16384 + (srow + 64 * (pi - 4)) * 64 + sch * 8);
;             __builtin_amdgcn_sched_barrier(0);
;           }
;         }
;         if (ks + 2 < 4) { ldfrag(ks + 2, slot); __builtin_amdgcn_sched_barrier(0); }
;       }
	s_add_i32 s13, s12, 0xffff8000
	s_and_b32 s13, s13, 0x8000
	s_lshl_b32 s13, s13, 1
	v_lshl_or_b32 v128, v143, 1, s13
	v_lshl_add_u32 v149, v147, 1, s13
	s_and_b32 s98, s12, 0x8000
	s_lshl_b32 s98, s98, 1
	s_waitcnt lgkmcnt(7)
	v_mfma_f32_32x32x16_bf16 v[64:79], v[178:181], v[194:197], v[64:79]
	v_add3_u32 v226, s98, v162, v156
	s_waitcnt lgkmcnt(6)
	v_mfma_f32_32x32x16_bf16 v[112:127], v[178:181], v[198:201], v[112:127]
	v_readfirstlane_b32 s100, v226
	s_mov_b32 s20, m0
	s_add_i32 m0, s100, 0x8000
	s_nop 0
	global_load_lds_dwordx4 v[160:161], off
	v_mfma_f32_32x32x16_bf16 v[32:47], v[182:185], v[194:197], v[32:47]
	v_lshl_add_u64 v[178:179], v[160:161], 0, s[2:3]
	s_add_i32 m0, s100, 0xa000
	s_nop 0
	global_load_lds_dwordx4 v[178:179], off
	v_mfma_f32_32x32x16_bf16 v[96:111], v[182:185], v[198:201], v[96:111]
	v_lshl_add_u64 v[180:181], v[160:161], 0, s[4:5]
	s_add_i32 m0, s100, 0xc000
	s_nop 0
	global_load_lds_dwordx4 v[180:181], off
	v_mfma_f32_32x32x16_bf16 v[16:31], v[186:189], v[194:197], v[16:31]
	v_lshl_add_u64 v[178:179], v[160:161], 0, s[6:7]
	s_add_i32 m0, s100, 0xe000
	s_nop 0
	global_load_lds_dwordx4 v[178:179], off
	s_mov_b32 m0, s20
	v_mfma_f32_32x32x16_bf16 v[80:95], v[186:189], v[198:201], v[80:95]
	v_mfma_f32_32x32x16_bf16 v[0:15], v[190:193], v[194:197], v[0:15]
	v_mfma_f32_32x32x16_bf16 v[48:63], v[190:193], v[198:201], v[48:63]
	v_lshl_add_u64 v[160:161], v[160:161], 0, s[8:9]
	v_add_u32_e32 v177, v128, v175
	ds_read_b128 v[178:181], v177
	ds_read_b128 v[182:185], v177 offset:4096
	ds_read_b128 v[186:189], v177 offset:8192
	ds_read_b128 v[190:193], v177 offset:12288
	v_add_u32_e32 v177, v149, v175
	ds_read_b128 v[194:197], v177 offset:32768
	ds_read_b128 v[198:201], v177 offset:36864
	s_waitcnt lgkmcnt(7)
	v_mfma_f32_32x32x16_bf16 v[64:79], v[202:205], v[218:221], v[64:79]
	s_waitcnt lgkmcnt(6)
	v_mfma_f32_32x32x16_bf16 v[112:127], v[202:205], v[222:225], v[112:127]
	v_mfma_f32_32x32x16_bf16 v[32:47], v[206:209], v[218:221], v[32:47]
	v_mfma_f32_32x32x16_bf16 v[96:111], v[206:209], v[222:225], v[96:111]
	v_mfma_f32_32x32x16_bf16 v[16:31], v[210:213], v[218:221], v[16:31]
	v_mfma_f32_32x32x16_bf16 v[80:95], v[210:213], v[222:225], v[80:95]
	v_mfma_f32_32x32x16_bf16 v[0:15], v[214:217], v[218:221], v[0:15]
	v_mfma_f32_32x32x16_bf16 v[48:63], v[214:217], v[222:225], v[48:63]
	v_add_u32_e32 v128, v128, v176
	ds_read_b128 v[202:205], v128
	ds_read_b128 v[206:209], v128 offset:4096
	ds_read_b128 v[210:213], v128 offset:8192
	ds_read_b128 v[214:217], v128 offset:12288
	v_add_u32_e32 v128, v149, v176
	ds_read_b128 v[218:221], v128 offset:32768
	ds_read_b128 v[222:225], v128 offset:36864
	v_readlane_b32 s98, v254, 28
	v_readlane_b32 s99, v254, 24
	s_nop 1
	s_add_i32 s98, s19, s98
	s_mul_hi_i32 s100, s98, 0xb21642c9
	s_add_i32 s100, s100, s98
	s_lshr_b32 s101, s100, 31
	s_ashr_i32 s100, s100, 6
	s_add_i32 s100, s100, s101
	s_lshl_b32 s101, s100, 3
	s_or_b32 s101, s101, s99
	s_cmp_lt_i32 s101, 32
	s_cselect_b32 s98, s98, s19
	s_mul_hi_i32 s100, s98, 0xb21642c9
	s_add_i32 s100, s100, s98
	s_lshr_b32 s101, s100, 31
	s_ashr_i32 s100, s100, 6
	s_add_i32 s100, s100, s101
	s_mul_i32 s101, s100, 0x5c
	s_sub_i32 s101, s98, s101
	s_lshl_b32 s100, s100, 3
	s_or_b32 s100, s100, s99
	s_and_b32 s99, s101, 3
	s_lshl_b32 s100, s100, 2
	s_or_b32 s100, s100, s99
	s_ashr_i32 s101, s101, 2
	v_lshrrev_b32_e32 v236, 6, v252
	v_and_b32_e32 v237, 3, v236
	v_lshl_add_u32 v237, v237, 6, v135
	v_mov_b32_e32 v238, s101
	v_mov_b32_e32 v239, s100
	v_cmp_gt_u32_e32 vcc, 4, v236
	v_readlane_b32 s98, v253, 29
	v_readlane_b32 s99, v253, 30
	v_readlane_b32 s100, v253, 31
	v_readlane_b32 s101, v253, 32
	v_cndmask_b32_e32 v238, v238, v239, vcc
	v_lshl_add_u32 v237, v238, 8, v237
	v_mov_b32_e32 v240, s100
	v_mov_b32_e32 v241, s101
	v_mov_b32_e32 v242, s98
	v_mov_b32_e32 v243, s99
	v_cndmask_b32_e32 v240, v240, v242, vcc
	v_cndmask_b32_e32 v241, v241, v243, vcc
	v_mad_u64_u32 v[240:241], s[98:99], v237, s0, v[240:241]
	global_load_dword v236, v[240:241], off
	global_load_dword v237, v[240:241], off offset:128
	s_waitcnt lgkmcnt(7)
	v_mfma_f32_32x32x16_bf16 v[64:79], v[178:181], v[194:197], v[64:79]
	s_waitcnt lgkmcnt(6)
	v_mfma_f32_32x32x16_bf16 v[112:127], v[178:181], v[198:201], v[112:127]
	v_mfma_f32_32x32x16_bf16 v[32:47], v[182:185], v[194:197], v[32:47]
	v_mfma_f32_32x32x16_bf16 v[96:111], v[182:185], v[198:201], v[96:111]
	v_mfma_f32_32x32x16_bf16 v[16:31], v[186:189], v[194:197], v[16:31]
	v_mfma_f32_32x32x16_bf16 v[80:95], v[186:189], v[198:201], v[80:95]
	v_mfma_f32_32x32x16_bf16 v[0:15], v[190:193], v[194:197], v[0:15]
	v_mfma_f32_32x32x16_bf16 v[48:63], v[190:193], v[198:201], v[48:63]
	s_waitcnt lgkmcnt(1)
	v_mfma_f32_32x32x16_bf16 v[64:79], v[202:205], v[218:221], v[64:79]
	s_waitcnt lgkmcnt(0)
	v_mfma_f32_32x32x16_bf16 v[112:127], v[202:205], v[222:225], v[112:127]
	v_mfma_f32_32x32x16_bf16 v[32:47], v[206:209], v[218:221], v[32:47]
	v_mfma_f32_32x32x16_bf16 v[96:111], v[206:209], v[222:225], v[96:111]
	v_mfma_f32_32x32x16_bf16 v[16:31], v[210:213], v[218:221], v[16:31]
	v_mfma_f32_32x32x16_bf16 v[80:95], v[210:213], v[222:225], v[80:95]
	v_mfma_f32_32x32x16_bf16 v[0:15], v[214:217], v[218:221], v[0:15]
	v_mfma_f32_32x32x16_bf16 v[48:63], v[214:217], v[222:225], v[48:63]
	s_waitcnt vmcnt(2)
	s_barrier
; __device__ __forceinline__ int accrow(int reg, int lh) { return (reg & 3) + 8 * (reg >> 2) + 4 * lh; }
; template <int EPI, int PN>
; __device__ void gemm_phase(const Params& p, const u16* __restrict__ A, const u16* __restrict__ Bt, int nNt, char* smem) {
;     ...
;         for (int i = 0; i < 4; ++i) {
;           acc[i][0] = mfma32(af[slot][i], bf[slot][0], acc[i][0]);
;           acc[i][1] = mfma32(af[slot][i], bf[slot][1], acc[i][1]);
;           __builtin_amdgcn_sched_barrier(0);
;           if (pre && (i & 1) == 0) {
;             const int pi = ks * 2 + (i >> 1);
;             if (pi < 4) glds16(Ag0 + (size_t)pi * 64 * LDK + (kt + 1) * 64, st + (srow + 64 * pi) * 64 + sch * 8);
;             else glds16(Bg0 + (size_t)(pi - 4) * 64 * LDK + (kt + 1) * 64, st + 16384 + (srow + 64 * (pi - 4)) * 64 + sch * 8);
;             __builtin_amdgcn_sched_barrier(0);
;           }
;         }
;         if (ks + 2 < 4) { ldfrag(ks + 2, slot); __builtin_amdgcn_sched_barrier(0); }
;       }
;     ...
;     } else {
; #pragma unroll
;       for (int i = 0; i < 4; ++i)
; #pragma unroll
;         for (int j = 0; j < 2; ++j)
; #pragma unroll
;           for (int r = 0; r < 16; ++r) *(u16*)(et + (i * 32 + accrow(r, lhE)) * 144 + (j * 32 + lrE) * 2) = f2bf(acc[i][j][r]);
	ds_read_b128 v[158:161], v164
	ds_read_b128 v[178:181], v164 offset:4096
	ds_read_b128 v[182:185], v164 offset:8192
	ds_read_b128 v[186:189], v164 offset:12288
	ds_read_b128 v[190:193], v165
	ds_read_b128 v[194:197], v165 offset:4096
	ds_read_b128 v[198:201], v166
	ds_read_b128 v[202:205], v166 offset:4096
	ds_read_b128 v[206:209], v166 offset:8192
	ds_read_b128 v[210:213], v166 offset:12288
	ds_read_b128 v[214:217], v168
	ds_read_b128 v[218:221], v168 offset:4096
	s_waitcnt lgkmcnt(7)
	v_mfma_f32_32x32x16_bf16 v[64:79], v[158:161], v[190:193], v[64:79]
	s_waitcnt lgkmcnt(6)
	v_mfma_f32_32x32x16_bf16 v[112:127], v[158:161], v[194:197], v[112:127]
	v_mfma_f32_32x32x16_bf16 v[32:47], v[178:181], v[190:193], v[32:47]
	v_mfma_f32_32x32x16_bf16 v[96:111], v[178:181], v[194:197], v[96:111]
	v_mfma_f32_32x32x16_bf16 v[16:31], v[182:185], v[190:193], v[16:31]
	v_mfma_f32_32x32x16_bf16 v[80:95], v[182:185], v[194:197], v[80:95]
	v_mfma_f32_32x32x16_bf16 v[0:15], v[186:189], v[190:193], v[0:15]
	v_mfma_f32_32x32x16_bf16 v[48:63], v[186:189], v[194:197], v[48:63]
	ds_read_b128 v[158:161], v169
	ds_read_b128 v[178:181], v169 offset:4096
	ds_read_b128 v[182:185], v169 offset:8192
	ds_read_b128 v[186:189], v169 offset:12288
	ds_read_b128 v[190:193], v170
	ds_read_b128 v[194:197], v170 offset:4096
	s_waitcnt lgkmcnt(7)
	v_mfma_f32_32x32x16_bf16 v[64:79], v[198:201], v[214:217], v[64:79]
	s_waitcnt lgkmcnt(6)
	v_mfma_f32_32x32x16_bf16 v[112:127], v[198:201], v[218:221], v[112:127]
	v_mfma_f32_32x32x16_bf16 v[32:47], v[202:205], v[214:217], v[32:47]
	v_mfma_f32_32x32x16_bf16 v[96:111], v[202:205], v[218:221], v[96:111]
	v_mfma_f32_32x32x16_bf16 v[16:31], v[206:209], v[214:217], v[16:31]
	v_mfma_f32_32x32x16_bf16 v[80:95], v[206:209], v[218:221], v[80:95]
	v_mfma_f32_32x32x16_bf16 v[0:15], v[210:213], v[214:217], v[0:15]
	v_mfma_f32_32x32x16_bf16 v[48:63], v[210:213], v[218:221], v[48:63]
	ds_read_b128 v[198:201], v171
	ds_read_b128 v[202:205], v171 offset:4096
	ds_read_b128 v[206:209], v171 offset:8192
	ds_read_b128 v[210:213], v171 offset:12288
	ds_read_b128 v[214:217], v172
	ds_read_b128 v[218:221], v172 offset:4096
	s_waitcnt lgkmcnt(7)
	v_mfma_f32_32x32x16_bf16 v[64:79], v[158:161], v[190:193], v[64:79]
	s_waitcnt lgkmcnt(6)
	v_mfma_f32_32x32x16_bf16 v[112:127], v[158:161], v[194:197], v[112:127]
	v_mfma_f32_32x32x16_bf16 v[32:47], v[178:181], v[190:193], v[32:47]
	v_mfma_f32_32x32x16_bf16 v[96:111], v[178:181], v[194:197], v[96:111]
	v_mfma_f32_32x32x16_bf16 v[16:31], v[182:185], v[190:193], v[16:31]
	v_mfma_f32_32x32x16_bf16 v[80:95], v[182:185], v[194:197], v[80:95]
	v_mfma_f32_32x32x16_bf16 v[0:15], v[186:189], v[190:193], v[0:15]
	v_mfma_f32_32x32x16_bf16 v[48:63], v[186:189], v[194:197], v[48:63]
	s_waitcnt lgkmcnt(1)
	v_mfma_f32_32x32x16_bf16 v[64:79], v[198:201], v[214:217], v[64:79]
	s_waitcnt lgkmcnt(0)
	v_mfma_f32_32x32x16_bf16 v[112:127], v[198:201], v[218:221], v[112:127]
	v_mfma_f32_32x32x16_bf16 v[32:47], v[202:205], v[214:217], v[32:47]
	v_mfma_f32_32x32x16_bf16 v[96:111], v[202:205], v[218:221], v[96:111]
	v_mfma_f32_32x32x16_bf16 v[16:31], v[206:209], v[214:217], v[16:31]
	v_mfma_f32_32x32x16_bf16 v[80:95], v[206:209], v[218:221], v[80:95]
	v_mfma_f32_32x32x16_bf16 v[0:15], v[210:213], v[214:217], v[0:15]
	v_mfma_f32_32x32x16_bf16 v[48:63], v[210:213], v[218:221], v[48:63]
	v_mov_b32_e32 v128, v139
	v_mov_b32_e32 v161, v137
	v_mov_b32_e32 v177, v135
	s_barrier
	s_nop 0
	v_lshl_add_u32 v160, s11, 8, v145
	s_ashr_i32 s11, s10, 31
	s_lshl_b64 s[10:11], s[10:11], 8
	v_mov_b32_e32 v159, s11
	v_or_b32_e32 v158, s10, v134
	v_cmp_gt_i32_e32 vcc, s14, v160
	s_and_saveexec_b64 s[10:11], vcc
	s_xor_b64 s[10:11], exec, s[10:11]
	s_cbranch_execz .LBB0_132
	v_lshlrev_b32_e32 v149, 1, v161
	v_mul_lo_u32 v128, v128, s15
	v_add3_u32 v128, v163, v149, v128
	v_cvt_pk_bf16_f32 v0, v0, s0
	v_cvt_pk_bf16_f32 v64, v64, s0
	v_cvt_pk_bf16_f32 v32, v32, s0
	v_cvt_pk_bf16_f32 v16, v16, s0
	ds_write_b16 v128, v0 offset:13824
	v_cvt_pk_bf16_f32 v0, v1, s0
	ds_write_b16 v128, v64
	v_cvt_pk_bf16_f32 v64, v65, s0
	ds_write_b16 v128, v32 offset:4608
	v_cvt_pk_bf16_f32 v32, v33, s0
	ds_write_b16 v128, v16 offset:9216
	v_cvt_pk_bf16_f32 v16, v17, s0
	ds_write_b16 v128, v0 offset:13968
	v_cvt_pk_bf16_f32 v0, v2, s0
	ds_write_b16 v128, v64 offset:144
	v_cvt_pk_bf16_f32 v64, v66, s0
	ds_write_b16 v128, v32 offset:4752
	v_cvt_pk_bf16_f32 v32, v34, s0
	ds_write_b16 v128, v16 offset:9360
	v_cvt_pk_bf16_f32 v16, v18, s0
	ds_write_b16 v128, v0 offset:14112
	v_cvt_pk_bf16_f32 v0, v3, s0
	ds_write_b16 v128, v64 offset:288
	v_cvt_pk_bf16_f32 v64, v67, s0
	ds_write_b16 v128, v32 offset:4896
	v_cvt_pk_bf16_f32 v32, v35, s0
	ds_write_b16 v128, v16 offset:9504
	v_cvt_pk_bf16_f32 v16, v19, s0
	ds_write_b16 v128, v0 offset:14256
	v_cvt_pk_bf16_f32 v0, v4, s0
	ds_write_b16 v128, v64 offset:432
	v_cvt_pk_bf16_f32 v64, v68, s0
	ds_write_b16 v128, v32 offset:5040
	v_cvt_pk_bf16_f32 v32, v36, s0
	ds_write_b16 v128, v16 offset:9648
	v_cvt_pk_bf16_f32 v16, v20, s0
	ds_write_b16 v128, v0 offset:14976
	v_cvt_pk_bf16_f32 v0, v5, s0
	ds_write_b16 v128, v64 offset:1152
	v_cvt_pk_bf16_f32 v64, v69, s0
	ds_write_b16 v128, v32 offset:5760
	v_cvt_pk_bf16_f32 v32, v37, s0
	ds_write_b16 v128, v16 offset:10368
	v_cvt_pk_bf16_f32 v16, v21, s0
	ds_write_b16 v128, v0 offset:15120
	v_cvt_pk_bf16_f32 v0, v6, s0
	ds_write_b16 v128, v64 offset:1296
	v_cvt_pk_bf16_f32 v64, v70, s0
	ds_write_b16 v128, v32 offset:5904
	v_cvt_pk_bf16_f32 v32, v38, s0
	ds_write_b16 v128, v16 offset:10512
	v_cvt_pk_bf16_f32 v16, v22, s0
	ds_write_b16 v128, v0 offset:15264
	v_cvt_pk_bf16_f32 v0, v7, s0
	ds_write_b16 v128, v64 offset:1440
; __device__ __forceinline__ int accrow(int reg, int lh) { return (reg & 3) + 8 * (reg >> 2) + 4 * lh; }
; template <int EPI, int PN>
; __device__ void gemm_phase(const Params& p, const u16* __restrict__ A, const u16* __restrict__ Bt, int nNt, char* smem) {
;     ...
;     } else {
; #pragma unroll
;       for (int i = 0; i < 4; ++i)
; #pragma unroll
;         for (int j = 0; j < 2; ++j)
; #pragma unroll
;           for (int r = 0; r < 16; ++r) *(u16*)(et + (i * 32 + accrow(r, lhE)) * 144 + (j * 32 + lrE) * 2) = f2bf(acc[i][j][r]);
	v_cvt_pk_bf16_f32 v64, v71, s0
	ds_write_b16 v128, v32 offset:6048
	v_cvt_pk_bf16_f32 v32, v39, s0
	ds_write_b16 v128, v16 offset:10656
	v_cvt_pk_bf16_f32 v16, v23, s0
	ds_write_b16 v128, v0 offset:15408
	v_cvt_pk_bf16_f32 v0, v8, s0
	ds_write_b16 v128, v64 offset:1584
	v_cvt_pk_bf16_f32 v64, v72, s0
	ds_write_b16 v128, v32 offset:6192
	v_cvt_pk_bf16_f32 v32, v40, s0
	ds_write_b16 v128, v16 offset:10800
	v_cvt_pk_bf16_f32 v16, v24, s0
	ds_write_b16 v128, v0 offset:16128
	v_cvt_pk_bf16_f32 v0, v9, s0
	ds_write_b16 v128, v64 offset:2304
	v_cvt_pk_bf16_f32 v64, v73, s0
	ds_write_b16 v128, v32 offset:6912
	v_cvt_pk_bf16_f32 v32, v41, s0
	ds_write_b16 v128, v16 offset:11520
	v_cvt_pk_bf16_f32 v16, v25, s0
	ds_write_b16 v128, v0 offset:16272
	v_cvt_pk_bf16_f32 v0, v10, s0
	ds_write_b16 v128, v64 offset:2448
	v_cvt_pk_bf16_f32 v64, v74, s0
	ds_write_b16 v128, v32 offset:7056
	v_cvt_pk_bf16_f32 v32, v42, s0
	ds_write_b16 v128, v16 offset:11664
	v_cvt_pk_bf16_f32 v16, v26, s0
	ds_write_b16 v128, v0 offset:16416
	v_cvt_pk_bf16_f32 v0, v11, s0
	ds_write_b16 v128, v64 offset:2592
	v_cvt_pk_bf16_f32 v64, v75, s0
	ds_write_b16 v128, v32 offset:7200
	v_cvt_pk_bf16_f32 v32, v43, s0
	ds_write_b16 v128, v16 offset:11808
	v_cvt_pk_bf16_f32 v16, v27, s0
	ds_write_b16 v128, v0 offset:16560
	v_cvt_pk_bf16_f32 v0, v12, s0
	ds_write_b16 v128, v64 offset:2736
	v_cvt_pk_bf16_f32 v64, v76, s0
	ds_write_b16 v128, v32 offset:7344
	v_cvt_pk_bf16_f32 v32, v44, s0
	ds_write_b16 v128, v16 offset:11952
	v_cvt_pk_bf16_f32 v16, v28, s0
	ds_write_b16 v128, v0 offset:17280
	v_cvt_pk_bf16_f32 v0, v13, s0
	ds_write_b16 v128, v64 offset:3456
	v_cvt_pk_bf16_f32 v64, v77, s0
	ds_write_b16 v128, v32 offset:8064
	v_cvt_pk_bf16_f32 v32, v45, s0
	ds_write_b16 v128, v16 offset:12672
	v_cvt_pk_bf16_f32 v16, v29, s0
	ds_write_b16 v128, v0 offset:17424
	v_cvt_pk_bf16_f32 v0, v14, s0
	ds_write_b16 v128, v64 offset:3600
	v_cvt_pk_bf16_f32 v64, v78, s0
	ds_write_b16 v128, v32 offset:8208
	v_cvt_pk_bf16_f32 v32, v46, s0
	ds_write_b16 v128, v16 offset:12816
	v_cvt_pk_bf16_f32 v16, v30, s0
	ds_write_b16 v128, v0 offset:17568
	v_cvt_pk_bf16_f32 v0, v15, s0
	ds_write_b16 v128, v64 offset:3744
	v_cvt_pk_bf16_f32 v64, v79, s0
	ds_write_b16 v128, v32 offset:8352
	v_cvt_pk_bf16_f32 v32, v47, s0
	ds_write_b16 v128, v16 offset:12960
	v_cvt_pk_bf16_f32 v16, v31, s0
	ds_write_b16 v128, v0 offset:17712
	v_cvt_pk_bf16_f32 v0, v48, s0
	ds_write_b16 v128, v64 offset:3888
	v_cvt_pk_bf16_f32 v64, v112, s0
	ds_write_b16 v128, v32 offset:8496
	v_cvt_pk_bf16_f32 v32, v96, s0
	ds_write_b16 v128, v16 offset:13104
	v_cvt_pk_bf16_f32 v16, v80, s0
	ds_write_b16 v128, v0 offset:13888
	v_cvt_pk_bf16_f32 v0, v49, s0
	ds_write_b16 v128, v64 offset:64
	v_cvt_pk_bf16_f32 v64, v113, s0
	ds_write_b16 v128, v32 offset:4672
	v_cvt_pk_bf16_f32 v32, v97, s0
	ds_write_b16 v128, v16 offset:9280
	v_cvt_pk_bf16_f32 v16, v81, s0
	ds_write_b16 v128, v0 offset:14032
	v_cvt_pk_bf16_f32 v0, v50, s0
	ds_write_b16 v128, v64 offset:208
	v_cvt_pk_bf16_f32 v64, v114, s0
	ds_write_b16 v128, v32 offset:4816
	v_cvt_pk_bf16_f32 v32, v98, s0
	ds_write_b16 v128, v16 offset:9424
	v_cvt_pk_bf16_f32 v16, v82, s0
	ds_write_b16 v128, v0 offset:14176
	v_cvt_pk_bf16_f32 v0, v51, s0
	ds_write_b16 v128, v64 offset:352
	v_cvt_pk_bf16_f32 v64, v115, s0
	ds_write_b16 v128, v32 offset:4960
	v_cvt_pk_bf16_f32 v32, v99, s0
	ds_write_b16 v128, v16 offset:9568
	v_cvt_pk_bf16_f32 v16, v83, s0
	ds_write_b16 v128, v0 offset:14320
	v_cvt_pk_bf16_f32 v0, v52, s0
	ds_write_b16 v128, v64 offset:496
	v_cvt_pk_bf16_f32 v64, v116, s0
	ds_write_b16 v128, v32 offset:5104
	v_cvt_pk_bf16_f32 v32, v100, s0
	ds_write_b16 v128, v16 offset:9712
	v_cvt_pk_bf16_f32 v16, v84, s0
	ds_write_b16 v128, v0 offset:15040
	v_cvt_pk_bf16_f32 v0, v53, s0
	ds_write_b16 v128, v64 offset:1216
	v_cvt_pk_bf16_f32 v64, v117, s0
	ds_write_b16 v128, v32 offset:5824
	v_cvt_pk_bf16_f32 v32, v101, s0
	ds_write_b16 v128, v16 offset:10432
	v_cvt_pk_bf16_f32 v16, v85, s0
	ds_write_b16 v128, v0 offset:15184
	v_cvt_pk_bf16_f32 v0, v54, s0
	ds_write_b16 v128, v64 offset:1360
	v_cvt_pk_bf16_f32 v64, v118, s0
	ds_write_b16 v128, v32 offset:5968
	v_cvt_pk_bf16_f32 v32, v102, s0
	ds_write_b16 v128, v16 offset:10576
	v_cvt_pk_bf16_f32 v16, v86, s0
	ds_write_b16 v128, v0 offset:15328
	v_cvt_pk_bf16_f32 v0, v55, s0
	ds_write_b16 v128, v64 offset:1504
	v_cvt_pk_bf16_f32 v64, v119, s0
	ds_write_b16 v128, v32 offset:6112
	v_cvt_pk_bf16_f32 v32, v103, s0
	ds_write_b16 v128, v16 offset:10720
	v_cvt_pk_bf16_f32 v16, v87, s0
	ds_write_b16 v128, v0 offset:15472
	v_cvt_pk_bf16_f32 v0, v56, s0
	ds_write_b16 v128, v64 offset:1648
	v_cvt_pk_bf16_f32 v64, v120, s0
	ds_write_b16 v128, v32 offset:6256
	v_cvt_pk_bf16_f32 v32, v104, s0
	ds_write_b16 v128, v16 offset:10864
	v_cvt_pk_bf16_f32 v16, v88, s0
	ds_write_b16 v128, v0 offset:16192
	v_cvt_pk_bf16_f32 v0, v57, s0
	ds_write_b16 v128, v64 offset:2368
	v_cvt_pk_bf16_f32 v64, v121, s0
	ds_write_b16 v128, v32 offset:6976
	v_cvt_pk_bf16_f32 v32, v105, s0
	ds_write_b16 v128, v16 offset:11584
	v_cvt_pk_bf16_f32 v16, v89, s0
	ds_write_b16 v128, v0 offset:16336
	v_cvt_pk_bf16_f32 v0, v58, s0
	ds_write_b16 v128, v64 offset:2512
	v_cvt_pk_bf16_f32 v64, v122, s0
	ds_write_b16 v128, v32 offset:7120
	v_cvt_pk_bf16_f32 v32, v106, s0
	ds_write_b16 v128, v16 offset:11728
	v_cvt_pk_bf16_f32 v16, v90, s0
	ds_write_b16 v128, v0 offset:16480
	v_cvt_pk_bf16_f32 v0, v59, s0
	ds_write_b16 v128, v64 offset:2656
	v_cvt_pk_bf16_f32 v64, v123, s0
	ds_write_b16 v128, v32 offset:7264
	v_cvt_pk_bf16_f32 v32, v107, s0
	ds_write_b16 v128, v16 offset:11872
	v_cvt_pk_bf16_f32 v16, v91, s0
	ds_write_b16 v128, v0 offset:16624
; __device__ __forceinline__ int accrow(int reg, int lh) { return (reg & 3) + 8 * (reg >> 2) + 4 * lh; }
; template <int EPI, int PN>
; __device__ void gemm_phase(const Params& p, const u16* __restrict__ A, const u16* __restrict__ Bt, int nNt, char* smem) {
;     ...
;     } else {
; #pragma unroll
;       for (int i = 0; i < 4; ++i)
; #pragma unroll
;         for (int j = 0; j < 2; ++j)
; #pragma unroll
;           for (int r = 0; r < 16; ++r) *(u16*)(et + (i * 32 + accrow(r, lhE)) * 144 + (j * 32 + lrE) * 2) = f2bf(acc[i][j][r]);
; #pragma unroll
;       for (int it = 0; it < 16; ++it) {
;         const int c = it * 64 + laneE, row = c >> 3, seg = c & 7;
;         const uint4 v = *(const uint4*)(et + row * 144 + seg * 16);
;         if (EPI == 0) *(uint4*)(p.proj + (row0 + row) * NPROJ + col0 + seg * 8) = v;
;         else *(uint4*)(p.qp + (row0 + row) * DM + col0 + seg * 8) = v;
;       }
	v_cvt_pk_bf16_f32 v0, v60, s0
	ds_write_b16 v128, v64 offset:2800
	v_cvt_pk_bf16_f32 v64, v124, s0
	ds_write_b16 v128, v32 offset:7408
	v_cvt_pk_bf16_f32 v32, v108, s0
	ds_write_b16 v128, v16 offset:12016
	v_cvt_pk_bf16_f32 v16, v92, s0
	ds_write_b16 v128, v0 offset:17344
	v_cvt_pk_bf16_f32 v0, v61, s0
	ds_write_b16 v128, v64 offset:3520
	v_cvt_pk_bf16_f32 v64, v125, s0
	ds_write_b16 v128, v32 offset:8128
	v_cvt_pk_bf16_f32 v32, v109, s0
	ds_write_b16 v128, v16 offset:12736
	v_cvt_pk_bf16_f32 v16, v93, s0
	ds_write_b16 v128, v0 offset:17488
	v_cvt_pk_bf16_f32 v0, v62, s0
	ds_write_b16 v128, v64 offset:3664
	v_cvt_pk_bf16_f32 v64, v126, s0
	ds_write_b16 v128, v32 offset:8272
	v_cvt_pk_bf16_f32 v32, v110, s0
	ds_write_b16 v128, v16 offset:12880
	v_cvt_pk_bf16_f32 v16, v94, s0
	ds_write_b16 v128, v0 offset:17632
	v_cvt_pk_bf16_f32 v0, v63, s0
	ds_write_b16 v128, v64 offset:3808
	v_cvt_pk_bf16_f32 v64, v127, s0
	ds_write_b16 v128, v32 offset:8416
	v_cvt_pk_bf16_f32 v32, v111, s0
	ds_write_b16 v128, v16 offset:13024
	v_cvt_pk_bf16_f32 v16, v95, s0
	ds_write_b16 v128, v0 offset:17776
	v_lshlrev_b32_e32 v0, 4, v177
	ds_write_b16 v128, v64 offset:3952
	ds_write_b16 v128, v32 offset:8560
	ds_write_b16 v128, v16 offset:13168
	v_and_b32_e32 v128, 0x70, v0
	v_add_u32_e32 v0, v163, v128
	v_ashrrev_i32_e32 v6, 3, v177
	v_readlane_b32 s36, v253, 39
	v_mad_u64_u32 v[2:3], s[12:13], v6, s16, v[0:1]
	v_ashrrev_i32_e32 v7, 31, v6
	v_readlane_b32 s40, v253, 43
	v_readlane_b32 s41, v253, 44
	ds_read_b128 v[2:5], v2
	v_lshl_add_u64 v[6:7], v[158:159], 0, v[6:7]
	v_mov_b64_e32 v[10:11], s[40:41]
	v_ashrrev_i32_e32 v161, 31, v160
	v_mad_u64_u32 v[8:9], s[12:13], v6, s17, v[10:11]
	v_mad_i32_i24 v9, v7, s17, v9
	v_lshlrev_b64 v[12:13], 1, v[160:161]
	v_add_u32_e32 v1, 64, v177
	v_lshl_add_u64 v[6:7], v[8:9], 0, v[12:13]
	v_ashrrev_i32_e32 v16, 3, v1
	v_lshl_add_u64 v[14:15], v[6:7], 0, v[128:129]
	v_mad_u64_u32 v[6:7], s[12:13], v16, s16, v[0:1]
	v_ashrrev_i32_e32 v17, 31, v16
	ds_read_b128 v[6:9], v6
	s_waitcnt lgkmcnt(1)
	global_store_dwordx4 v[14:15], v[2:5], off
	v_add_u32_e32 v1, 0x80, v177
	v_readlane_b32 s37, v253, 40
	v_lshl_add_u64 v[2:3], v[158:159], 0, v[16:17]
	v_mad_u64_u32 v[4:5], s[12:13], v2, s17, v[10:11]
	v_mad_i32_i24 v5, v3, s17, v5
	v_lshl_add_u64 v[2:3], v[4:5], 0, v[12:13]
	v_lshl_add_u64 v[2:3], v[2:3], 0, v[128:129]
	s_waitcnt lgkmcnt(0)
	global_store_dwordx4 v[2:3], v[6:9], off
	v_readlane_b32 s38, v253, 41
	v_readlane_b32 s39, v253, 42
	v_ashrrev_i32_e32 v6, 3, v1
	v_mad_u64_u32 v[2:3], s[12:13], v6, s16, v[0:1]
	v_ashrrev_i32_e32 v7, 31, v6
	ds_read_b128 v[2:5], v2
	v_lshl_add_u64 v[6:7], v[158:159], 0, v[6:7]
	v_mad_u64_u32 v[8:9], s[12:13], v6, s17, v[10:11]
	v_mad_i32_i24 v9, v7, s17, v9
	v_add_u32_e32 v1, 0xc0, v177
	v_lshl_add_u64 v[6:7], v[8:9], 0, v[12:13]
	v_ashrrev_i32_e32 v16, 3, v1
	v_lshl_add_u64 v[14:15], v[6:7], 0, v[128:129]
	v_mad_u64_u32 v[6:7], s[12:13], v16, s16, v[0:1]
	v_ashrrev_i32_e32 v17, 31, v16
	ds_read_b128 v[6:9], v6
	s_waitcnt lgkmcnt(1)
	global_store_dwordx4 v[14:15], v[2:5], off
	v_add_u32_e32 v1, 0x100, v177
	v_readlane_b32 s42, v253, 45
	v_lshl_add_u64 v[2:3], v[158:159], 0, v[16:17]
	v_mad_u64_u32 v[4:5], s[12:13], v2, s17, v[10:11]
	v_mad_i32_i24 v5, v3, s17, v5
	v_lshl_add_u64 v[2:3], v[4:5], 0, v[12:13]
	v_lshl_add_u64 v[2:3], v[2:3], 0, v[128:129]
	s_waitcnt lgkmcnt(0)
	global_store_dwordx4 v[2:3], v[6:9], off
	v_readlane_b32 s43, v253, 46
	v_readlane_b32 s44, v253, 47
	v_ashrrev_i32_e32 v6, 3, v1
	v_mad_u64_u32 v[2:3], s[12:13], v6, s16, v[0:1]
	v_ashrrev_i32_e32 v7, 31, v6
	ds_read_b128 v[2:5], v2
	v_lshl_add_u64 v[6:7], v[158:159], 0, v[6:7]
	v_mad_u64_u32 v[8:9], s[12:13], v6, s17, v[10:11]
	v_mad_i32_i24 v9, v7, s17, v9
	v_add_u32_e32 v1, 0x140, v177
	v_lshl_add_u64 v[6:7], v[8:9], 0, v[12:13]
	v_ashrrev_i32_e32 v16, 3, v1
	v_lshl_add_u64 v[14:15], v[6:7], 0, v[128:129]
	v_mad_u64_u32 v[6:7], s[12:13], v16, s16, v[0:1]
	v_ashrrev_i32_e32 v17, 31, v16
	ds_read_b128 v[6:9], v6
	s_waitcnt lgkmcnt(1)
	global_store_dwordx4 v[14:15], v[2:5], off
	v_add_u32_e32 v1, 0x180, v177
	v_readlane_b32 s45, v253, 48
	v_lshl_add_u64 v[2:3], v[158:159], 0, v[16:17]
	v_mad_u64_u32 v[4:5], s[12:13], v2, s17, v[10:11]
	v_mad_i32_i24 v5, v3, s17, v5
	v_lshl_add_u64 v[2:3], v[4:5], 0, v[12:13]
	v_lshl_add_u64 v[2:3], v[2:3], 0, v[128:129]
	s_waitcnt lgkmcnt(0)
; template <int EPI, int PN>
; __device__ void gemm_phase(const Params& p, const u16* __restrict__ A, const u16* __restrict__ Bt, int nNt, char* smem) {
;     ...
;       for (int it = 0; it < 16; ++it) {
;         const int c = it * 64 + laneE, row = c >> 3, seg = c & 7;
;         const uint4 v = *(const uint4*)(et + row * 144 + seg * 16);
;         if (EPI == 0) *(uint4*)(p.proj + (row0 + row) * NPROJ + col0 + seg * 8) = v;
;         else *(uint4*)(p.qp + (row0 + row) * DM + col0 + seg * 8) = v;
;       }
	global_store_dwordx4 v[2:3], v[6:9], off
	v_readlane_b32 s46, v253, 49
	v_readlane_b32 s47, v253, 50
	v_ashrrev_i32_e32 v6, 3, v1
	v_mad_u64_u32 v[2:3], s[12:13], v6, s16, v[0:1]
	v_ashrrev_i32_e32 v7, 31, v6
	ds_read_b128 v[2:5], v2
	v_lshl_add_u64 v[6:7], v[158:159], 0, v[6:7]
	v_mad_u64_u32 v[8:9], s[12:13], v6, s17, v[10:11]
	v_mad_i32_i24 v9, v7, s17, v9
	v_add_u32_e32 v1, 0x1c0, v177
	v_lshl_add_u64 v[6:7], v[8:9], 0, v[12:13]
	v_ashrrev_i32_e32 v16, 3, v1
	v_lshl_add_u64 v[14:15], v[6:7], 0, v[128:129]
	v_mad_u64_u32 v[6:7], s[12:13], v16, s16, v[0:1]
	v_ashrrev_i32_e32 v17, 31, v16
	ds_read_b128 v[6:9], v6
	s_waitcnt lgkmcnt(1)
	global_store_dwordx4 v[14:15], v[2:5], off
	v_add_u32_e32 v1, 0x200, v177
	v_readlane_b32 s48, v253, 51
	v_lshl_add_u64 v[2:3], v[158:159], 0, v[16:17]
	v_mad_u64_u32 v[4:5], s[12:13], v2, s17, v[10:11]
	v_mad_i32_i24 v5, v3, s17, v5
	v_lshl_add_u64 v[2:3], v[4:5], 0, v[12:13]
	v_lshl_add_u64 v[2:3], v[2:3], 0, v[128:129]
	s_waitcnt lgkmcnt(0)
	global_store_dwordx4 v[2:3], v[6:9], off
	v_readlane_b32 s49, v253, 52
	v_readlane_b32 s50, v253, 53
	v_ashrrev_i32_e32 v6, 3, v1
	v_mad_u64_u32 v[2:3], s[12:13], v6, s16, v[0:1]
	v_ashrrev_i32_e32 v7, 31, v6
	ds_read_b128 v[2:5], v2
	v_lshl_add_u64 v[6:7], v[158:159], 0, v[6:7]
	v_mad_u64_u32 v[8:9], s[12:13], v6, s17, v[10:11]
	v_mad_i32_i24 v9, v7, s17, v9
	v_add_u32_e32 v1, 0x240, v177
	v_lshl_add_u64 v[6:7], v[8:9], 0, v[12:13]
	v_ashrrev_i32_e32 v16, 3, v1
	v_lshl_add_u64 v[14:15], v[6:7], 0, v[128:129]
	v_mad_u64_u32 v[6:7], s[12:13], v16, s16, v[0:1]
	v_ashrrev_i32_e32 v17, 31, v16
	ds_read_b128 v[6:9], v6
	s_waitcnt lgkmcnt(1)
	global_store_dwordx4 v[14:15], v[2:5], off
	v_add_u32_e32 v1, 0x280, v177
	v_readlane_b32 s51, v253, 54
	v_lshl_add_u64 v[2:3], v[158:159], 0, v[16:17]
	v_mad_u64_u32 v[4:5], s[12:13], v2, s17, v[10:11]
	v_mad_i32_i24 v5, v3, s17, v5
	v_lshl_add_u64 v[2:3], v[4:5], 0, v[12:13]
	v_lshl_add_u64 v[2:3], v[2:3], 0, v[128:129]
	s_waitcnt lgkmcnt(0)
	global_store_dwordx4 v[2:3], v[6:9], off
	s_nop 1
	v_ashrrev_i32_e32 v6, 3, v1
	v_mad_u64_u32 v[2:3], s[12:13], v6, s16, v[0:1]
	v_ashrrev_i32_e32 v7, 31, v6
	ds_read_b128 v[2:5], v2
	v_lshl_add_u64 v[6:7], v[158:159], 0, v[6:7]
	v_mad_u64_u32 v[8:9], s[12:13], v6, s17, v[10:11]
	v_mad_i32_i24 v9, v7, s17, v9
	v_add_u32_e32 v1, 0x2c0, v177
	v_lshl_add_u64 v[6:7], v[8:9], 0, v[12:13]
	v_ashrrev_i32_e32 v16, 3, v1
	v_lshl_add_u64 v[14:15], v[6:7], 0, v[128:129]
	v_mad_u64_u32 v[6:7], s[12:13], v16, s16, v[0:1]
	v_ashrrev_i32_e32 v17, 31, v16
	ds_read_b128 v[6:9], v6
	s_waitcnt lgkmcnt(1)
	global_store_dwordx4 v[14:15], v[2:5], off
	v_add_u32_e32 v1, 0x300, v177
	s_nop 0
	v_lshl_add_u64 v[2:3], v[158:159], 0, v[16:17]
	v_mad_u64_u32 v[4:5], s[12:13], v2, s17, v[10:11]
	v_mad_i32_i24 v5, v3, s17, v5
	v_lshl_add_u64 v[2:3], v[4:5], 0, v[12:13]
	v_lshl_add_u64 v[2:3], v[2:3], 0, v[128:129]
	s_waitcnt lgkmcnt(0)
	global_store_dwordx4 v[2:3], v[6:9], off
	s_nop 1
	v_ashrrev_i32_e32 v6, 3, v1
	v_mad_u64_u32 v[2:3], s[12:13], v6, s16, v[0:1]
	v_ashrrev_i32_e32 v7, 31, v6
	ds_read_b128 v[2:5], v2
	v_lshl_add_u64 v[6:7], v[158:159], 0, v[6:7]
	v_mad_u64_u32 v[8:9], s[12:13], v6, s17, v[10:11]
	v_mad_i32_i24 v9, v7, s17, v9
	v_add_u32_e32 v1, 0x340, v177
	v_lshl_add_u64 v[6:7], v[8:9], 0, v[12:13]
	v_ashrrev_i32_e32 v16, 3, v1
	v_lshl_add_u64 v[14:15], v[6:7], 0, v[128:129]
	v_mad_u64_u32 v[6:7], s[12:13], v16, s16, v[0:1]
	v_ashrrev_i32_e32 v17, 31, v16
	ds_read_b128 v[6:9], v6
	s_waitcnt lgkmcnt(1)
	global_store_dwordx4 v[14:15], v[2:5], off
	v_add_u32_e32 v1, 0x380, v177
	s_nop 0
	v_lshl_add_u64 v[2:3], v[158:159], 0, v[16:17]
	v_mad_u64_u32 v[4:5], s[12:13], v2, s17, v[10:11]
	v_mad_i32_i24 v5, v3, s17, v5
	v_lshl_add_u64 v[2:3], v[4:5], 0, v[12:13]
	v_lshl_add_u64 v[2:3], v[2:3], 0, v[128:129]
	s_waitcnt lgkmcnt(0)
	global_store_dwordx4 v[2:3], v[6:9], off
	s_nop 1
	v_ashrrev_i32_e32 v6, 3, v1
	v_mad_u64_u32 v[2:3], s[12:13], v6, s16, v[0:1]
	v_ashrrev_i32_e32 v7, 31, v6
	ds_read_b128 v[2:5], v2
	v_lshl_add_u64 v[6:7], v[158:159], 0, v[6:7]
	v_mad_u64_u32 v[8:9], s[12:13], v6, s17, v[10:11]
	v_add_u32_e32 v1, 0x3c0, v177
	v_mad_i32_i24 v9, v7, s17, v9
	v_ashrrev_i32_e32 v16, 3, v1
	v_lshl_add_u64 v[6:7], v[8:9], 0, v[12:13]
	v_mad_u64_u32 v[0:1], s[12:13], v16, s16, v[0:1]
	v_ashrrev_i32_e32 v17, 31, v16
	v_lshl_add_u64 v[14:15], v[6:7], 0, v[128:129]
	ds_read_b128 v[6:9], v0
	v_lshl_add_u64 v[0:1], v[158:159], 0, v[16:17]
	s_waitcnt lgkmcnt(1)
	global_store_dwordx4 v[14:15], v[2:5], off
	s_nop 1
	v_mad_u64_u32 v[2:3], s[12:13], v0, s17, v[10:11]
	v_mad_i32_i24 v3, v1, s17, v3
	v_lshl_add_u64 v[0:1], v[2:3], 0, v[12:13]
	v_lshl_add_u64 v[0:1], v[0:1], 0, v[128:129]
	s_waitcnt lgkmcnt(0)
	global_store_dwordx4 v[0:1], v[6:9], off

; template <int EPI, int PN>
; __device__ void gemm_phase(const Params& p, const u16* __restrict__ A, const u16* __restrict__ Bt, int nNt, char* smem) {
;     ...
;     for (int kt = 0; kt < 32; ++kt) {
;       asm volatile("s_waitcnt vmcnt(0)" ::: "memory");
;       __builtin_amdgcn_s_barrier();
;       const u16* Ab = ring + (kt & 1) * STG;
;       const u16* Bb = Ab + 16384;
;       u16* st = ring + ((kt + 1) & 1) * STG;
;       const bool pre = (kt + 1 < 32);
;       s16x8 af[2][4], bf[2][2];
;       auto ldfrag = [&](int ks, int slot) {
; #pragma unroll
;         for (int i = 0; i < 4; ++i) {
;           const int row = wr * 128 + i * 32 + lr;
;           af[slot][i] = *(const s16x8*)(Ab + row * 64 + (((ks * 2 + lh) ^ ((row >> 1) & 7)) * 8));
;         }
; #pragma unroll
;         for (int j = 0; j < 2; ++j) {
;           const int rowb = nh * 128 + wc * 64 + j * 32 + lr;
;           bf[slot][j] = *(const s16x8*)(Bb + rowb * 64 + (((ks * 2 + lh) ^ ((rowb >> 1) & 7)) * 8));
;         }
;       };
;       ldfrag(0, 0);
;       ldfrag(1, 1);
;       __builtin_amdgcn_sched_barrier(0);
; #pragma unroll
;       for (int ks = 0; ks < 4; ++ks) {
;         const int slot = ks & 1;
; #pragma unroll
;         for (int i = 0; i < 4; ++i) {
;           acc[i][0] = mfma32(af[slot][i], bf[slot][0], acc[i][0]);
;           acc[i][1] = mfma32(af[slot][i], bf[slot][1], acc[i][1]);
;           __builtin_amdgcn_sched_barrier(0);
;           if (pre && (i & 1) == 0) {
;             const int pi = ks * 2 + (i >> 1);
;             if (pi < 4) glds16(Ag0 + (size_t)pi * 64 * LDK + (kt + 1) * 64, st + (srow + 64 * pi) * 64 + sch * 8);
;             else glds16(Bg0 + (size_t)(pi - 4) * 64 * LDK + (kt + 1) * 64, st + 16384 + (srow + 64 * (pi - 4)) * 64 + sch * 8);
;             __builtin_amdgcn_sched_barrier(0);
;           }
;         }
;         if (ks + 2 < 4) { ldfrag(ks + 2, slot); __builtin_amdgcn_sched_barrier(0); }
;       }
.Lrot723_loop:
	s_add_i32 s15, s11, 0xffff8000
	s_and_b32 s15, s15, 0x8000
	s_lshl_b32 s15, s15, 1
	v_lshl_or_b32 v128, v143, 1, s15
	v_lshl_add_u32 v149, v147, 1, s15
	s_and_b32 s98, s11, 0x8000
	s_lshl_b32 s98, s98, 1
	s_waitcnt lgkmcnt(7)
	v_mfma_f32_32x32x16_bf16 v[112:127], v[178:181], v[194:197], v[112:127]
	v_add3_u32 v226, s98, v162, v156
	s_waitcnt lgkmcnt(6)
	v_mfma_f32_32x32x16_bf16 v[96:111], v[178:181], v[198:201], v[96:111]
	v_readfirstlane_b32 s100, v226
	s_mov_b32 s16, m0
	s_add_i32 m0, s100, 0x8000
	s_nop 0
	global_load_lds_dwordx4 v[160:161], off
	v_mfma_f32_32x32x16_bf16 v[80:95], v[182:185], v[194:197], v[80:95]
	v_lshl_add_u64 v[178:179], v[160:161], 0, s[2:3]
	s_add_i32 m0, s100, 0xa000
	s_nop 0
	global_load_lds_dwordx4 v[178:179], off
	v_mfma_f32_32x32x16_bf16 v[64:79], v[182:185], v[198:201], v[64:79]
	v_lshl_add_u64 v[180:181], v[160:161], 0, s[4:5]
	s_add_i32 m0, s100, 0xc000
	s_nop 0
	global_load_lds_dwordx4 v[180:181], off
	v_mfma_f32_32x32x16_bf16 v[48:63], v[186:189], v[194:197], v[48:63]
	v_lshl_add_u64 v[178:179], v[160:161], 0, s[6:7]
	s_add_i32 m0, s100, 0xe000
	s_nop 0
	global_load_lds_dwordx4 v[178:179], off
	s_mov_b32 m0, s16
	v_mfma_f32_32x32x16_bf16 v[32:47], v[186:189], v[198:201], v[32:47]
	v_mfma_f32_32x32x16_bf16 v[16:31], v[190:193], v[194:197], v[16:31]
	v_mfma_f32_32x32x16_bf16 v[0:15], v[190:193], v[198:201], v[0:15]
	v_lshl_add_u64 v[160:161], v[160:161], 0, s[8:9]
	v_add_u32_e32 v177, v128, v175
	ds_read_b128 v[178:181], v177
	ds_read_b128 v[182:185], v177 offset:4096
	ds_read_b128 v[186:189], v177 offset:8192
	ds_read_b128 v[190:193], v177 offset:12288
	v_add_u32_e32 v177, v149, v175
	ds_read_b128 v[194:197], v177 offset:32768
	ds_read_b128 v[198:201], v177 offset:36864
	s_waitcnt lgkmcnt(7)
	v_mfma_f32_32x32x16_bf16 v[112:127], v[202:205], v[218:221], v[112:127]
	s_waitcnt lgkmcnt(6)
	v_mfma_f32_32x32x16_bf16 v[96:111], v[202:205], v[222:225], v[96:111]
	v_mfma_f32_32x32x16_bf16 v[80:95], v[206:209], v[218:221], v[80:95]
	v_mfma_f32_32x32x16_bf16 v[64:79], v[206:209], v[222:225], v[64:79]
	v_mfma_f32_32x32x16_bf16 v[48:63], v[210:213], v[218:221], v[48:63]
	v_mfma_f32_32x32x16_bf16 v[32:47], v[210:213], v[222:225], v[32:47]
	v_mfma_f32_32x32x16_bf16 v[16:31], v[214:217], v[218:221], v[16:31]
	v_mfma_f32_32x32x16_bf16 v[0:15], v[214:217], v[222:225], v[0:15]
	v_add_u32_e32 v128, v128, v176
	ds_read_b128 v[202:205], v128
	ds_read_b128 v[206:209], v128 offset:4096
	ds_read_b128 v[210:213], v128 offset:8192
	ds_read_b128 v[214:217], v128 offset:12288
	v_add_u32_e32 v128, v149, v176
	ds_read_b128 v[218:221], v128 offset:32768
	ds_read_b128 v[222:225], v128 offset:36864
	s_waitcnt lgkmcnt(7)
	v_mfma_f32_32x32x16_bf16 v[112:127], v[178:181], v[194:197], v[112:127]
	s_waitcnt lgkmcnt(6)
	v_mfma_f32_32x32x16_bf16 v[96:111], v[178:181], v[198:201], v[96:111]
	v_mfma_f32_32x32x16_bf16 v[80:95], v[182:185], v[194:197], v[80:95]
	v_mfma_f32_32x32x16_bf16 v[64:79], v[182:185], v[198:201], v[64:79]
	v_mfma_f32_32x32x16_bf16 v[48:63], v[186:189], v[194:197], v[48:63]
	v_mfma_f32_32x32x16_bf16 v[32:47], v[186:189], v[198:201], v[32:47]
	v_mfma_f32_32x32x16_bf16 v[16:31], v[190:193], v[194:197], v[16:31]
	v_mfma_f32_32x32x16_bf16 v[0:15], v[190:193], v[198:201], v[0:15]
	v_lshl_or_b32 v227, v143, 1, s98
	v_lshl_add_u32 v229, v147, 1, s98
	v_add_u32_e32 v228, v227, v173
	v_add_u32_e32 v230, v229, v173
	s_waitcnt vmcnt(0) lgkmcnt(0)
	s_barrier
	ds_read_b128 v[178:181], v228
	ds_read_b128 v[182:185], v228 offset:4096
	ds_read_b128 v[186:189], v228 offset:8192
	ds_read_b128 v[190:193], v228 offset:12288
	ds_read_b128 v[194:197], v230 offset:32768
	ds_read_b128 v[198:201], v230 offset:36864
	v_add3_u32 v226, s15, v162, v156
	v_mfma_f32_32x32x16_bf16 v[112:127], v[202:205], v[218:221], v[112:127]
	v_readfirstlane_b32 s99, v226
	s_mov_b32 s16, m0
	s_mov_b32 m0, s99
	s_nop 0
	global_load_lds_dwordx4 v[158:159], off
	v_mfma_f32_32x32x16_bf16 v[96:111], v[202:205], v[222:225], v[96:111]
	v_lshl_add_u64 v[232:233], v[158:159], 0, s[2:3]
	s_add_i32 m0, s99, 0x2000
	s_nop 0
	global_load_lds_dwordx4 v[232:233], off
	v_mfma_f32_32x32x16_bf16 v[80:95], v[206:209], v[218:221], v[80:95]
	v_lshl_add_u64 v[234:235], v[158:159], 0, s[4:5]
	s_add_i32 m0, s99, 0x4000
	s_nop 0
	global_load_lds_dwordx4 v[234:235], off
	v_mfma_f32_32x32x16_bf16 v[64:79], v[206:209], v[222:225], v[64:79]
	v_lshl_add_u64 v[232:233], v[158:159], 0, s[6:7]
	s_add_i32 m0, s99, 0x6000
	s_nop 0
	global_load_lds_dwordx4 v[232:233], off
	s_mov_b32 m0, s16
	v_mfma_f32_32x32x16_bf16 v[48:63], v[210:213], v[218:221], v[48:63]
	v_mfma_f32_32x32x16_bf16 v[32:47], v[210:213], v[222:225], v[32:47]
	v_mfma_f32_32x32x16_bf16 v[16:31], v[214:217], v[218:221], v[16:31]
	v_mfma_f32_32x32x16_bf16 v[0:15], v[214:217], v[222:225], v[0:15]
	v_add_u32_e32 v228, v227, v174
	v_add_u32_e32 v230, v229, v174
	ds_read_b128 v[202:205], v228
	ds_read_b128 v[206:209], v228 offset:4096
	ds_read_b128 v[210:213], v228 offset:8192
	ds_read_b128 v[214:217], v228 offset:12288
	ds_read_b128 v[218:221], v230 offset:32768
	ds_read_b128 v[222:225], v230 offset:36864
	s_add_i32 s11, s11, 0x8000
	v_lshl_add_u64 v[158:159], v[158:159], 0, s[8:9]
	s_cmp_eq_u32 s11, 0xf8000
	s_cbranch_scc0 .Lrot723_loop
; template <int EPI, int PN>
; __device__ void gemm_phase(const Params& p, const u16* __restrict__ A, const u16* __restrict__ Bt, int nNt, char* smem) {
;     ...
;   for (int q = jb;; q += NJ) {
;     const int pl = q / (4 * PN), w = q % (4 * PN);
;     const int gp = pl * 8 + xcd;
;     if (gp >= npatch) break;
;     const int mt = (gp / npn) * 4 + (w & 3), nt = (gp % npn) * PN + (w >> 2);
;     const int gch = sch ^ ((srow >> 1) & 7);
;     const u16* Ag0 = A + (size_t)(mt * 256 + srow) * LDK + gch * 8;
;     const u16* Bg0 = Bt + (size_t)(nt * 256 + srow) * LDK + gch * 8;
;     ...
;     for (int kt = 0; kt < 32; ++kt) {
;       asm volatile("s_waitcnt vmcnt(0)" ::: "memory");
;       __builtin_amdgcn_s_barrier();
;       const u16* Ab = ring + (kt & 1) * STG;
;       const u16* Bb = Ab + 16384;
;       u16* st = ring + ((kt + 1) & 1) * STG;
;       const bool pre = (kt + 1 < 32);
;       s16x8 af[2][4], bf[2][2];
;       auto ldfrag = [&](int ks, int slot) {
; #pragma unroll
;         for (int i = 0; i < 4; ++i) {
;           const int row = wr * 128 + i * 32 + lr;
;           af[slot][i] = *(const s16x8*)(Ab + row * 64 + (((ks * 2 + lh) ^ ((row >> 1) & 7)) * 8));
;         }
; #pragma unroll
;         for (int j = 0; j < 2; ++j) {
;           const int rowb = nh * 128 + wc * 64 + j * 32 + lr;
;           bf[slot][j] = *(const s16x8*)(Bb + rowb * 64 + (((ks * 2 + lh) ^ ((rowb >> 1) & 7)) * 8));
;         }
;       };
;       ldfrag(0, 0);
;       ldfrag(1, 1);
;       __builtin_amdgcn_sched_barrier(0);
; #pragma unroll
;       for (int ks = 0; ks < 4; ++ks) {
;         const int slot = ks & 1;
; #pragma unroll
;         for (int i = 0; i < 4; ++i) {
;           acc[i][0] = mfma32(af[slot][i], bf[slot][0], acc[i][0]);
;           acc[i][1] = mfma32(af[slot][i], bf[slot][1], acc[i][1]);
;           __builtin_amdgcn_sched_barrier(0);
;           if (pre && (i & 1) == 0) {
;             const int pi = ks * 2 + (i >> 1);
;             if (pi < 4) glds16(Ag0 + (size_t)pi * 64 * LDK + (kt + 1) * 64, st + (srow + 64 * pi) * 64 + sch * 8);
;             else glds16(Bg0 + (size_t)(pi - 4) * 64 * LDK + (kt + 1) * 64, st + 16384 + (srow + 64 * (pi - 4)) * 64 + sch * 8);
;             __builtin_amdgcn_sched_barrier(0);
;           }
;         }
;         if (ks + 2 < 4) { ldfrag(ks + 2, slot); __builtin_amdgcn_sched_barrier(0); }
;       }
	s_add_i32 s15, s11, 0xffff8000
	s_and_b32 s15, s15, 0x8000
	s_lshl_b32 s15, s15, 1
	v_lshl_or_b32 v128, v143, 1, s15
	v_lshl_add_u32 v149, v147, 1, s15
	s_and_b32 s98, s11, 0x8000
	s_lshl_b32 s98, s98, 1
	s_waitcnt lgkmcnt(7)
	v_mfma_f32_32x32x16_bf16 v[112:127], v[178:181], v[194:197], v[112:127]
	v_add3_u32 v226, s98, v162, v156
	s_waitcnt lgkmcnt(6)
	v_mfma_f32_32x32x16_bf16 v[96:111], v[178:181], v[198:201], v[96:111]
	v_readfirstlane_b32 s100, v226
	s_mov_b32 s16, m0
	s_add_i32 m0, s100, 0x8000
	s_nop 0
	global_load_lds_dwordx4 v[160:161], off
	v_mfma_f32_32x32x16_bf16 v[80:95], v[182:185], v[194:197], v[80:95]
	v_lshl_add_u64 v[178:179], v[160:161], 0, s[2:3]
	s_add_i32 m0, s100, 0xa000
	s_nop 0
	global_load_lds_dwordx4 v[178:179], off
	v_mfma_f32_32x32x16_bf16 v[64:79], v[182:185], v[198:201], v[64:79]
	v_lshl_add_u64 v[180:181], v[160:161], 0, s[4:5]
	s_add_i32 m0, s100, 0xc000
	s_nop 0
	global_load_lds_dwordx4 v[180:181], off
	v_mfma_f32_32x32x16_bf16 v[48:63], v[186:189], v[194:197], v[48:63]
	v_lshl_add_u64 v[178:179], v[160:161], 0, s[6:7]
	s_add_i32 m0, s100, 0xe000
	s_nop 0
	global_load_lds_dwordx4 v[178:179], off
	s_mov_b32 m0, s16
	v_mfma_f32_32x32x16_bf16 v[32:47], v[186:189], v[198:201], v[32:47]
	v_mfma_f32_32x32x16_bf16 v[16:31], v[190:193], v[194:197], v[16:31]
	v_mfma_f32_32x32x16_bf16 v[0:15], v[190:193], v[198:201], v[0:15]
	v_lshl_add_u64 v[160:161], v[160:161], 0, s[8:9]
	v_add_u32_e32 v177, v128, v175
	ds_read_b128 v[178:181], v177
	ds_read_b128 v[182:185], v177 offset:4096
	ds_read_b128 v[186:189], v177 offset:8192
	ds_read_b128 v[190:193], v177 offset:12288
	v_add_u32_e32 v177, v149, v175
	ds_read_b128 v[194:197], v177 offset:32768
	ds_read_b128 v[198:201], v177 offset:36864
	s_waitcnt lgkmcnt(7)
	v_mfma_f32_32x32x16_bf16 v[112:127], v[202:205], v[218:221], v[112:127]
	s_waitcnt lgkmcnt(6)
	v_mfma_f32_32x32x16_bf16 v[96:111], v[202:205], v[222:225], v[96:111]
	v_mfma_f32_32x32x16_bf16 v[80:95], v[206:209], v[218:221], v[80:95]
	v_mfma_f32_32x32x16_bf16 v[64:79], v[206:209], v[222:225], v[64:79]
	v_mfma_f32_32x32x16_bf16 v[48:63], v[210:213], v[218:221], v[48:63]
	v_mfma_f32_32x32x16_bf16 v[32:47], v[210:213], v[222:225], v[32:47]
	v_mfma_f32_32x32x16_bf16 v[16:31], v[214:217], v[218:221], v[16:31]
	v_mfma_f32_32x32x16_bf16 v[0:15], v[214:217], v[222:225], v[0:15]
	v_add_u32_e32 v128, v128, v176
	ds_read_b128 v[202:205], v128
	ds_read_b128 v[206:209], v128 offset:4096
	ds_read_b128 v[210:213], v128 offset:8192
	ds_read_b128 v[214:217], v128 offset:12288
	v_add_u32_e32 v128, v149, v176
	ds_read_b128 v[218:221], v128 offset:32768
	ds_read_b128 v[222:225], v128 offset:36864
	v_readlane_b32 s98, v254, 28
	v_readlane_b32 s99, v254, 24
	s_nop 1
	s_add_i32 s98, s34, s98
	s_lshr_b32 s100, s98, 5
	s_lshl_b32 s101, s100, 3
	s_or_b32 s101, s101, s99
	s_cmp_lt_i32 s101, 32
	s_cselect_b32 s98, s98, s34
	s_lshr_b32 s100, s98, 5
	s_and_b32 s101, s98, 31
	s_lshl_b32 s100, s100, 3
	s_or_b32 s100, s100, s99
	s_and_b32 s99, s101, 3
	s_lshl_b32 s100, s100, 2
	s_or_b32 s100, s100, s99
	s_ashr_i32 s101, s101, 2
	v_lshrrev_b32_e32 v236, 6, v252
	v_and_b32_e32 v237, 3, v236
	v_lshl_add_u32 v237, v237, 6, v135
	v_mov_b32_e32 v238, s101
	v_mov_b32_e32 v239, s100
	v_cmp_gt_u32_e32 vcc, 4, v236
	v_readlane_b32 s98, v253, 29
	v_readlane_b32 s99, v253, 30
	v_readlane_b32 s100, v253, 35
	v_readlane_b32 s101, v253, 36
	v_cndmask_b32_e32 v238, v238, v239, vcc
	v_lshl_add_u32 v237, v238, 8, v237
	v_mov_b32_e32 v240, s100
	v_mov_b32_e32 v241, s101
	v_mov_b32_e32 v242, s98
	v_mov_b32_e32 v243, s99
	v_cndmask_b32_e32 v240, v240, v242, vcc
	v_cndmask_b32_e32 v241, v241, v243, vcc
	v_mad_u64_u32 v[240:241], s[98:99], v237, s0, v[240:241]
	global_load_dword v236, v[240:241], off
	global_load_dword v237, v[240:241], off offset:128
	s_waitcnt lgkmcnt(7)
	v_mfma_f32_32x32x16_bf16 v[112:127], v[178:181], v[194:197], v[112:127]
	s_waitcnt lgkmcnt(6)
	v_mfma_f32_32x32x16_bf16 v[96:111], v[178:181], v[198:201], v[96:111]
	v_mfma_f32_32x32x16_bf16 v[80:95], v[182:185], v[194:197], v[80:95]
	v_mfma_f32_32x32x16_bf16 v[64:79], v[182:185], v[198:201], v[64:79]
	v_mfma_f32_32x32x16_bf16 v[48:63], v[186:189], v[194:197], v[48:63]
	v_mfma_f32_32x32x16_bf16 v[32:47], v[186:189], v[198:201], v[32:47]
	v_mfma_f32_32x32x16_bf16 v[16:31], v[190:193], v[194:197], v[16:31]
	v_mfma_f32_32x32x16_bf16 v[0:15], v[190:193], v[198:201], v[0:15]
	s_waitcnt lgkmcnt(1)
	v_mfma_f32_32x32x16_bf16 v[112:127], v[202:205], v[218:221], v[112:127]
	s_waitcnt lgkmcnt(0)
	v_mfma_f32_32x32x16_bf16 v[96:111], v[202:205], v[222:225], v[96:111]
	v_mfma_f32_32x32x16_bf16 v[80:95], v[206:209], v[218:221], v[80:95]
	v_mfma_f32_32x32x16_bf16 v[64:79], v[206:209], v[222:225], v[64:79]
	v_mfma_f32_32x32x16_bf16 v[48:63], v[210:213], v[218:221], v[48:63]
	v_mfma_f32_32x32x16_bf16 v[32:47], v[210:213], v[222:225], v[32:47]
	v_mfma_f32_32x32x16_bf16 v[16:31], v[214:217], v[218:221], v[16:31]
	v_mfma_f32_32x32x16_bf16 v[0:15], v[214:217], v[222:225], v[0:15]
	s_waitcnt vmcnt(2)
	s_barrier
; __device__ __forceinline__ int accrow(int reg, int lh) { return (reg & 3) + 8 * (reg >> 2) + 4 * lh; }
; template <int EPI, int PN>
; __device__ void gemm_phase(const Params& p, const u16* __restrict__ A, const u16* __restrict__ Bt, int nNt, char* smem) {
;     ...
;       ldfrag(0, 0);
;       ldfrag(1, 1);
;       __builtin_amdgcn_sched_barrier(0);
; #pragma unroll
;       for (int ks = 0; ks < 4; ++ks) {
;         const int slot = ks & 1;
; #pragma unroll
;         for (int i = 0; i < 4; ++i) {
;           acc[i][0] = mfma32(af[slot][i], bf[slot][0], acc[i][0]);
;           acc[i][1] = mfma32(af[slot][i], bf[slot][1], acc[i][1]);
;           __builtin_amdgcn_sched_barrier(0);
;           if (pre && (i & 1) == 0) {
;             const int pi = ks * 2 + (i >> 1);
;             if (pi < 4) glds16(Ag0 + (size_t)pi * 64 * LDK + (kt + 1) * 64, st + (srow + 64 * pi) * 64 + sch * 8);
;             else glds16(Bg0 + (size_t)(pi - 4) * 64 * LDK + (kt + 1) * 64, st + 16384 + (srow + 64 * (pi - 4)) * 64 + sch * 8);
;             __builtin_amdgcn_sched_barrier(0);
;           }
;         }
;         if (ks + 2 < 4) { ldfrag(ks + 2, slot); __builtin_amdgcn_sched_barrier(0); }
;       }
;     }
;     __syncthreads();
;     ...
; #pragma unroll
;       for (int i = 0; i < 4; ++i)
; #pragma unroll
;         for (int j = 0; j < 2; ++j)
; #pragma unroll
;           for (int r = 0; r < 16; ++r) *(u16*)(et + (i * 32 + accrow(r, lhE)) * 144 + (j * 32 + lrE) * 2) = f2bf(acc[i][j][r]);
	ds_read_b128 v[158:161], v164
	ds_read_b128 v[178:181], v164 offset:4096
	ds_read_b128 v[182:185], v164 offset:8192
	ds_read_b128 v[186:189], v164 offset:12288
	ds_read_b128 v[190:193], v165
	ds_read_b128 v[194:197], v165 offset:4096
	ds_read_b128 v[198:201], v166
	ds_read_b128 v[202:205], v166 offset:4096
	ds_read_b128 v[206:209], v166 offset:8192
	ds_read_b128 v[210:213], v166 offset:12288
	ds_read_b128 v[214:217], v168
	ds_read_b128 v[218:221], v168 offset:4096
	s_waitcnt lgkmcnt(7)
	v_mfma_f32_32x32x16_bf16 v[112:127], v[158:161], v[190:193], v[112:127]
	s_waitcnt lgkmcnt(6)
	v_mfma_f32_32x32x16_bf16 v[96:111], v[158:161], v[194:197], v[96:111]
	v_mfma_f32_32x32x16_bf16 v[80:95], v[178:181], v[190:193], v[80:95]
	v_mfma_f32_32x32x16_bf16 v[64:79], v[178:181], v[194:197], v[64:79]
	v_mfma_f32_32x32x16_bf16 v[48:63], v[182:185], v[190:193], v[48:63]
	v_mfma_f32_32x32x16_bf16 v[32:47], v[182:185], v[194:197], v[32:47]
	v_mfma_f32_32x32x16_bf16 v[16:31], v[186:189], v[190:193], v[16:31]
	v_mfma_f32_32x32x16_bf16 v[0:15], v[186:189], v[194:197], v[0:15]
	ds_read_b128 v[158:161], v169
	ds_read_b128 v[178:181], v169 offset:4096
	ds_read_b128 v[182:185], v169 offset:8192
	ds_read_b128 v[186:189], v169 offset:12288
	ds_read_b128 v[190:193], v170
	ds_read_b128 v[194:197], v170 offset:4096
	s_waitcnt lgkmcnt(7)
	v_mfma_f32_32x32x16_bf16 v[112:127], v[198:201], v[214:217], v[112:127]
	s_waitcnt lgkmcnt(6)
	v_mfma_f32_32x32x16_bf16 v[96:111], v[198:201], v[218:221], v[96:111]
	v_mfma_f32_32x32x16_bf16 v[80:95], v[202:205], v[214:217], v[80:95]
	v_mfma_f32_32x32x16_bf16 v[64:79], v[202:205], v[218:221], v[64:79]
	v_mfma_f32_32x32x16_bf16 v[48:63], v[206:209], v[214:217], v[48:63]
	v_mfma_f32_32x32x16_bf16 v[32:47], v[206:209], v[218:221], v[32:47]
	v_mfma_f32_32x32x16_bf16 v[16:31], v[210:213], v[214:217], v[16:31]
	v_mfma_f32_32x32x16_bf16 v[0:15], v[210:213], v[218:221], v[0:15]
	ds_read_b128 v[198:201], v171
	ds_read_b128 v[202:205], v171 offset:4096
	ds_read_b128 v[206:209], v171 offset:8192
	ds_read_b128 v[210:213], v171 offset:12288
	ds_read_b128 v[214:217], v172
	ds_read_b128 v[218:221], v172 offset:4096
	s_waitcnt lgkmcnt(7)
	v_mfma_f32_32x32x16_bf16 v[112:127], v[158:161], v[190:193], v[112:127]
	s_waitcnt lgkmcnt(6)
	v_mfma_f32_32x32x16_bf16 v[96:111], v[158:161], v[194:197], v[96:111]
	v_mfma_f32_32x32x16_bf16 v[80:95], v[178:181], v[190:193], v[80:95]
	v_mfma_f32_32x32x16_bf16 v[64:79], v[178:181], v[194:197], v[64:79]
	v_mfma_f32_32x32x16_bf16 v[48:63], v[182:185], v[190:193], v[48:63]
	v_mfma_f32_32x32x16_bf16 v[32:47], v[182:185], v[194:197], v[32:47]
	v_mfma_f32_32x32x16_bf16 v[16:31], v[186:189], v[190:193], v[16:31]
	v_mfma_f32_32x32x16_bf16 v[0:15], v[186:189], v[194:197], v[0:15]
	s_waitcnt lgkmcnt(1)
	v_mfma_f32_32x32x16_bf16 v[112:127], v[198:201], v[214:217], v[112:127]
	s_waitcnt lgkmcnt(0)
	v_mfma_f32_32x32x16_bf16 v[96:111], v[198:201], v[218:221], v[96:111]
	v_mfma_f32_32x32x16_bf16 v[80:95], v[202:205], v[214:217], v[80:95]
	v_mfma_f32_32x32x16_bf16 v[64:79], v[202:205], v[218:221], v[64:79]
	v_mfma_f32_32x32x16_bf16 v[48:63], v[206:209], v[214:217], v[48:63]
	v_mfma_f32_32x32x16_bf16 v[32:47], v[206:209], v[218:221], v[32:47]
	v_mfma_f32_32x32x16_bf16 v[16:31], v[210:213], v[214:217], v[16:31]
	v_mfma_f32_32x32x16_bf16 v[0:15], v[210:213], v[218:221], v[0:15]
	v_mov_b32_e32 v149, v135
	v_mov_b32_e32 v128, v139
	v_mov_b32_e32 v158, v137
	s_barrier
	s_nop 7
	v_cvt_pk_bf16_f32 v0, v0, s0
	v_lshlrev_b32_e32 v158, 1, v158
	v_mul_lo_u32 v128, v128, s12
	v_add3_u32 v128, v163, v158, v128
	v_cvt_pk_bf16_f32 v112, v112, s0
	v_cvt_pk_bf16_f32 v96, v96, s0
	v_cvt_pk_bf16_f32 v80, v80, s0
	v_cvt_pk_bf16_f32 v64, v64, s0
	v_cvt_pk_bf16_f32 v48, v48, s0
	v_cvt_pk_bf16_f32 v32, v32, s0
	v_cvt_pk_bf16_f32 v16, v16, s0
	ds_write_b16 v128, v0 offset:13888
	v_cvt_pk_bf16_f32 v0, v1, s0
	ds_write_b16 v128, v112
	v_cvt_pk_bf16_f32 v112, v113, s0
	ds_write_b16 v128, v96 offset:64
	v_cvt_pk_bf16_f32 v96, v97, s0
	ds_write_b16 v128, v80 offset:4608
	v_cvt_pk_bf16_f32 v80, v81, s0
	ds_write_b16 v128, v64 offset:4672
	v_cvt_pk_bf16_f32 v64, v65, s0
	ds_write_b16 v128, v48 offset:9216
	v_cvt_pk_bf16_f32 v48, v49, s0
	ds_write_b16 v128, v32 offset:9280
	v_cvt_pk_bf16_f32 v32, v33, s0
	ds_write_b16 v128, v16 offset:13824
	v_cvt_pk_bf16_f32 v16, v17, s0
	ds_write_b16 v128, v0 offset:14032
	v_cvt_pk_bf16_f32 v0, v2, s0
	ds_write_b16 v128, v112 offset:144
	v_cvt_pk_bf16_f32 v112, v114, s0
	ds_write_b16 v128, v96 offset:208
	v_cvt_pk_bf16_f32 v96, v98, s0
	ds_write_b16 v128, v80 offset:4752
	v_cvt_pk_bf16_f32 v80, v82, s0
	ds_write_b16 v128, v64 offset:4816
	v_cvt_pk_bf16_f32 v64, v66, s0
	ds_write_b16 v128, v48 offset:9360
	v_cvt_pk_bf16_f32 v48, v50, s0
	ds_write_b16 v128, v32 offset:9424
	v_cvt_pk_bf16_f32 v32, v34, s0
	ds_write_b16 v128, v16 offset:13968
	v_cvt_pk_bf16_f32 v16, v18, s0
	ds_write_b16 v128, v0 offset:14176
	v_cvt_pk_bf16_f32 v0, v3, s0
	ds_write_b16 v128, v112 offset:288
	v_cvt_pk_bf16_f32 v112, v115, s0
	ds_write_b16 v128, v96 offset:352
	v_cvt_pk_bf16_f32 v96, v99, s0
	ds_write_b16 v128, v80 offset:4896
	v_cvt_pk_bf16_f32 v80, v83, s0
	ds_write_b16 v128, v64 offset:4960
	v_cvt_pk_bf16_f32 v64, v67, s0
	ds_write_b16 v128, v48 offset:9504
	v_cvt_pk_bf16_f32 v48, v51, s0
	ds_write_b16 v128, v32 offset:9568
	v_cvt_pk_bf16_f32 v32, v35, s0
	ds_write_b16 v128, v16 offset:14112
	v_cvt_pk_bf16_f32 v16, v19, s0
	ds_write_b16 v128, v0 offset:14320
	v_cvt_pk_bf16_f32 v0, v4, s0
	ds_write_b16 v128, v112 offset:432
	v_cvt_pk_bf16_f32 v112, v116, s0
	ds_write_b16 v128, v96 offset:496
	v_cvt_pk_bf16_f32 v96, v100, s0
	ds_write_b16 v128, v80 offset:5040
; __device__ __forceinline__ int accrow(int reg, int lh) { return (reg & 3) + 8 * (reg >> 2) + 4 * lh; }
; template <int EPI, int PN>
; __device__ void gemm_phase(const Params& p, const u16* __restrict__ A, const u16* __restrict__ Bt, int nNt, char* smem) {
;     ...
; #pragma unroll
;       for (int i = 0; i < 4; ++i)
; #pragma unroll
;         for (int j = 0; j < 2; ++j)
; #pragma unroll
;           for (int r = 0; r < 16; ++r) *(u16*)(et + (i * 32 + accrow(r, lhE)) * 144 + (j * 32 + lrE) * 2) = f2bf(acc[i][j][r]);
	v_cvt_pk_bf16_f32 v80, v84, s0
	ds_write_b16 v128, v64 offset:5104
	v_cvt_pk_bf16_f32 v64, v68, s0
	ds_write_b16 v128, v48 offset:9648
	v_cvt_pk_bf16_f32 v48, v52, s0
	ds_write_b16 v128, v32 offset:9712
	v_cvt_pk_bf16_f32 v32, v36, s0
	ds_write_b16 v128, v16 offset:14256
	v_cvt_pk_bf16_f32 v16, v20, s0
	ds_write_b16 v128, v0 offset:15040
	v_cvt_pk_bf16_f32 v0, v5, s0
	ds_write_b16 v128, v112 offset:1152
	v_cvt_pk_bf16_f32 v112, v117, s0
	ds_write_b16 v128, v96 offset:1216
	v_cvt_pk_bf16_f32 v96, v101, s0
	ds_write_b16 v128, v80 offset:5760
	v_cvt_pk_bf16_f32 v80, v85, s0
	ds_write_b16 v128, v64 offset:5824
	v_cvt_pk_bf16_f32 v64, v69, s0
	ds_write_b16 v128, v48 offset:10368
	v_cvt_pk_bf16_f32 v48, v53, s0
	ds_write_b16 v128, v32 offset:10432
	v_cvt_pk_bf16_f32 v32, v37, s0
	ds_write_b16 v128, v16 offset:14976
	v_cvt_pk_bf16_f32 v16, v21, s0
	ds_write_b16 v128, v0 offset:15184
	v_cvt_pk_bf16_f32 v0, v6, s0
	ds_write_b16 v128, v112 offset:1296
	v_cvt_pk_bf16_f32 v112, v118, s0
	ds_write_b16 v128, v96 offset:1360
	v_cvt_pk_bf16_f32 v96, v102, s0
	ds_write_b16 v128, v80 offset:5904
	v_cvt_pk_bf16_f32 v80, v86, s0
	ds_write_b16 v128, v64 offset:5968
	v_cvt_pk_bf16_f32 v64, v70, s0
	ds_write_b16 v128, v48 offset:10512
	v_cvt_pk_bf16_f32 v48, v54, s0
	ds_write_b16 v128, v32 offset:10576
	v_cvt_pk_bf16_f32 v32, v38, s0
	ds_write_b16 v128, v16 offset:15120
	v_cvt_pk_bf16_f32 v16, v22, s0
	ds_write_b16 v128, v0 offset:15328
	v_cvt_pk_bf16_f32 v0, v7, s0
	ds_write_b16 v128, v112 offset:1440
	v_cvt_pk_bf16_f32 v112, v119, s0
	ds_write_b16 v128, v96 offset:1504
	v_cvt_pk_bf16_f32 v96, v103, s0
	ds_write_b16 v128, v80 offset:6048
	v_cvt_pk_bf16_f32 v80, v87, s0
	ds_write_b16 v128, v64 offset:6112
	v_cvt_pk_bf16_f32 v64, v71, s0
	ds_write_b16 v128, v48 offset:10656
	v_cvt_pk_bf16_f32 v48, v55, s0
	ds_write_b16 v128, v32 offset:10720
	v_cvt_pk_bf16_f32 v32, v39, s0
	ds_write_b16 v128, v16 offset:15264
	v_cvt_pk_bf16_f32 v16, v23, s0
	ds_write_b16 v128, v0 offset:15472
	v_cvt_pk_bf16_f32 v0, v8, s0
	ds_write_b16 v128, v112 offset:1584
	v_cvt_pk_bf16_f32 v112, v120, s0
	ds_write_b16 v128, v96 offset:1648
	v_cvt_pk_bf16_f32 v96, v104, s0
	ds_write_b16 v128, v80 offset:6192
	v_cvt_pk_bf16_f32 v80, v88, s0
	ds_write_b16 v128, v64 offset:6256
	v_cvt_pk_bf16_f32 v64, v72, s0
	ds_write_b16 v128, v48 offset:10800
	v_cvt_pk_bf16_f32 v48, v56, s0
	ds_write_b16 v128, v32 offset:10864
	v_cvt_pk_bf16_f32 v32, v40, s0
	ds_write_b16 v128, v16 offset:15408
	v_cvt_pk_bf16_f32 v16, v24, s0
	ds_write_b16 v128, v0 offset:16192
	v_cvt_pk_bf16_f32 v0, v9, s0
	ds_write_b16 v128, v112 offset:2304
	v_cvt_pk_bf16_f32 v112, v121, s0
	ds_write_b16 v128, v96 offset:2368
	v_cvt_pk_bf16_f32 v96, v105, s0
	ds_write_b16 v128, v80 offset:6912
	v_cvt_pk_bf16_f32 v80, v89, s0
	ds_write_b16 v128, v64 offset:6976
	v_cvt_pk_bf16_f32 v64, v73, s0
	ds_write_b16 v128, v48 offset:11520
	v_cvt_pk_bf16_f32 v48, v57, s0
	ds_write_b16 v128, v32 offset:11584
	v_cvt_pk_bf16_f32 v32, v41, s0
	ds_write_b16 v128, v16 offset:16128
	v_cvt_pk_bf16_f32 v16, v25, s0
	ds_write_b16 v128, v0 offset:16336
	v_cvt_pk_bf16_f32 v0, v10, s0
	ds_write_b16 v128, v112 offset:2448
	v_cvt_pk_bf16_f32 v112, v122, s0
	ds_write_b16 v128, v96 offset:2512
	v_cvt_pk_bf16_f32 v96, v106, s0
	ds_write_b16 v128, v80 offset:7056
	v_cvt_pk_bf16_f32 v80, v90, s0
	ds_write_b16 v128, v64 offset:7120
	v_cvt_pk_bf16_f32 v64, v74, s0
	ds_write_b16 v128, v48 offset:11664
	v_cvt_pk_bf16_f32 v48, v58, s0
	ds_write_b16 v128, v32 offset:11728
	v_cvt_pk_bf16_f32 v32, v42, s0
	ds_write_b16 v128, v16 offset:16272
	v_cvt_pk_bf16_f32 v16, v26, s0
	ds_write_b16 v128, v0 offset:16480
	v_cvt_pk_bf16_f32 v0, v11, s0
	ds_write_b16 v128, v112 offset:2592
	v_cvt_pk_bf16_f32 v112, v123, s0
	ds_write_b16 v128, v96 offset:2656
	v_cvt_pk_bf16_f32 v96, v107, s0
	ds_write_b16 v128, v80 offset:7200
	v_cvt_pk_bf16_f32 v80, v91, s0
	ds_write_b16 v128, v64 offset:7264
	v_cvt_pk_bf16_f32 v64, v75, s0
	ds_write_b16 v128, v48 offset:11808
	v_cvt_pk_bf16_f32 v48, v59, s0
	ds_write_b16 v128, v32 offset:11872
	v_cvt_pk_bf16_f32 v32, v43, s0
	ds_write_b16 v128, v16 offset:16416
	v_cvt_pk_bf16_f32 v16, v27, s0
	ds_write_b16 v128, v0 offset:16624
	v_cvt_pk_bf16_f32 v0, v12, s0
	ds_write_b16 v128, v112 offset:2736
	v_cvt_pk_bf16_f32 v112, v124, s0
	ds_write_b16 v128, v96 offset:2800
	v_cvt_pk_bf16_f32 v96, v108, s0
	ds_write_b16 v128, v80 offset:7344
	v_cvt_pk_bf16_f32 v80, v92, s0
	ds_write_b16 v128, v64 offset:7408
	v_cvt_pk_bf16_f32 v64, v76, s0
	ds_write_b16 v128, v48 offset:11952
	v_cvt_pk_bf16_f32 v48, v60, s0
	ds_write_b16 v128, v32 offset:12016
	v_cvt_pk_bf16_f32 v32, v44, s0
	ds_write_b16 v128, v16 offset:16560
	v_cvt_pk_bf16_f32 v16, v28, s0
	ds_write_b16 v128, v0 offset:17344
	v_cvt_pk_bf16_f32 v0, v13, s0
	ds_write_b16 v128, v112 offset:3456
	v_cvt_pk_bf16_f32 v112, v125, s0
	ds_write_b16 v128, v96 offset:3520
	v_cvt_pk_bf16_f32 v96, v109, s0
	ds_write_b16 v128, v80 offset:8064
	v_cvt_pk_bf16_f32 v80, v93, s0
	ds_write_b16 v128, v64 offset:8128
	v_cvt_pk_bf16_f32 v64, v77, s0
	ds_write_b16 v128, v48 offset:12672
	v_cvt_pk_bf16_f32 v48, v61, s0
	ds_write_b16 v128, v32 offset:12736
	v_cvt_pk_bf16_f32 v32, v45, s0
	ds_write_b16 v128, v16 offset:17280
	v_cvt_pk_bf16_f32 v16, v29, s0
	ds_write_b16 v128, v0 offset:17488
	v_cvt_pk_bf16_f32 v0, v14, s0
	ds_write_b16 v128, v112 offset:3600
	v_cvt_pk_bf16_f32 v112, v126, s0
	ds_write_b16 v128, v96 offset:3664
	v_cvt_pk_bf16_f32 v96, v110, s0
	ds_write_b16 v128, v80 offset:8208
	v_cvt_pk_bf16_f32 v80, v94, s0
	ds_write_b16 v128, v64 offset:8272
	v_cvt_pk_bf16_f32 v64, v78, s0
	ds_write_b16 v128, v48 offset:12816
; __device__ __forceinline__ int accrow(int reg, int lh) { return (reg & 3) + 8 * (reg >> 2) + 4 * lh; }
; template <int EPI, int PN>
; __device__ void gemm_phase(const Params& p, const u16* __restrict__ A, const u16* __restrict__ Bt, int nNt, char* smem) {
;     ...
;           for (int r = 0; r < 16; ++r) *(u16*)(et + (i * 32 + accrow(r, lhE)) * 144 + (j * 32 + lrE) * 2) = f2bf(acc[i][j][r]);
; #pragma unroll
;       for (int it = 0; it < 16; ++it) {
;         const int c = it * 64 + laneE, row = c >> 3, seg = c & 7;
;         const uint4 v = *(const uint4*)(et + row * 144 + seg * 16);
;         if (EPI == 0) *(uint4*)(p.proj + (row0 + row) * NPROJ + col0 + seg * 8) = v;
;         else *(uint4*)(p.qp + (row0 + row) * DM + col0 + seg * 8) = v;
	v_cvt_pk_bf16_f32 v48, v62, s0
	ds_write_b16 v128, v32 offset:12880
	v_cvt_pk_bf16_f32 v32, v46, s0
	ds_write_b16 v128, v16 offset:17424
	v_cvt_pk_bf16_f32 v16, v30, s0
	ds_write_b16 v128, v0 offset:17632
	v_cvt_pk_bf16_f32 v0, v15, s0
	s_ashr_i32 s11, s10, 31
	ds_write_b16 v128, v112 offset:3744
	v_cvt_pk_bf16_f32 v112, v127, s0
	ds_write_b16 v128, v96 offset:3808
	v_cvt_pk_bf16_f32 v96, v111, s0
	ds_write_b16 v128, v80 offset:8352
	v_cvt_pk_bf16_f32 v80, v95, s0
	ds_write_b16 v128, v64 offset:8416
	v_cvt_pk_bf16_f32 v64, v79, s0
	ds_write_b16 v128, v48 offset:12960
	v_cvt_pk_bf16_f32 v48, v63, s0
	ds_write_b16 v128, v32 offset:13024
	v_cvt_pk_bf16_f32 v32, v47, s0
	ds_write_b16 v128, v16 offset:17568
	v_cvt_pk_bf16_f32 v16, v31, s0
	ds_write_b16 v128, v0 offset:17776
	v_lshlrev_b32_e32 v0, 4, v149
	s_lshl_b64 s[10:11], s[10:11], 8
	ds_write_b16 v128, v112 offset:3888
	ds_write_b16 v128, v96 offset:3952
	ds_write_b16 v128, v80 offset:8496
	ds_write_b16 v128, v64 offset:8560
	ds_write_b16 v128, v48 offset:13104
	ds_write_b16 v128, v32 offset:13168
	ds_write_b16 v128, v16 offset:17712
	v_and_b32_e32 v128, 0x70, v0
	v_ashrrev_i32_e32 v6, 3, v149
	v_mov_b32_e32 v9, s11
	v_or_b32_e32 v8, s10, v134
	v_add_u32_e32 v10, v163, v128
	v_ashrrev_i32_e32 v7, 31, v6
	v_lshl_add_u32 v4, s14, 8, v145
	v_mad_u64_u32 v[0:1], s[10:11], v6, s13, v[10:11]
	v_lshl_add_u64 v[6:7], v[8:9], 0, v[6:7]
	v_readlane_b32 s16, v253, 39
	v_ashrrev_i32_e32 v5, 31, v4
	v_lshlrev_b64 v[6:7], 12, v[6:7]
	v_readlane_b32 s26, v253, 49
	v_readlane_b32 s27, v253, 50
	ds_read_b128 v[0:3], v0
	v_lshlrev_b64 v[12:13], 1, v[4:5]
	v_lshl_add_u64 v[6:7], s[26:27], 0, v[6:7]
	v_lshl_add_u64 v[4:5], v[6:7], 0, v[12:13]
	v_lshl_add_u64 v[14:15], v[4:5], 0, v[128:129]
	v_add_u32_e32 v4, 64, v149
	v_ashrrev_i32_e32 v16, 3, v4
	v_mad_u64_u32 v[4:5], s[10:11], v16, s13, v[10:11]
	v_ashrrev_i32_e32 v17, 31, v16
	ds_read_b128 v[4:7], v4
	s_waitcnt lgkmcnt(1)
	global_store_dwordx4 v[14:15], v[0:3], off
	v_readlane_b32 s17, v253, 40
	v_readlane_b32 s18, v253, 41
	v_lshl_add_u64 v[0:1], v[8:9], 0, v[16:17]
	v_lshlrev_b64 v[0:1], 12, v[0:1]
	v_lshl_add_u64 v[0:1], s[26:27], 0, v[0:1]
	v_lshl_add_u64 v[0:1], v[0:1], 0, v[12:13]
	v_lshl_add_u64 v[0:1], v[0:1], 0, v[128:129]
	s_waitcnt lgkmcnt(0)
	global_store_dwordx4 v[0:1], v[4:7], off
	v_add_u32_e32 v0, 0x80, v149
	v_readlane_b32 s19, v253, 42
	v_ashrrev_i32_e32 v4, 3, v0
	v_ashrrev_i32_e32 v5, 31, v4
	v_mad_u64_u32 v[0:1], s[10:11], v4, s13, v[10:11]
	v_lshl_add_u64 v[4:5], v[8:9], 0, v[4:5]
	v_lshlrev_b64 v[4:5], 12, v[4:5]
	ds_read_b128 v[0:3], v0
	v_lshl_add_u64 v[4:5], s[26:27], 0, v[4:5]
	v_lshl_add_u64 v[4:5], v[4:5], 0, v[12:13]
	v_lshl_add_u64 v[14:15], v[4:5], 0, v[128:129]
	v_add_u32_e32 v4, 0xc0, v149
	v_ashrrev_i32_e32 v16, 3, v4
	v_mad_u64_u32 v[4:5], s[10:11], v16, s13, v[10:11]
	v_ashrrev_i32_e32 v17, 31, v16
	ds_read_b128 v[4:7], v4
	s_waitcnt lgkmcnt(1)
	global_store_dwordx4 v[14:15], v[0:3], off
	v_readlane_b32 s20, v253, 43
	v_readlane_b32 s21, v253, 44
	v_lshl_add_u64 v[0:1], v[8:9], 0, v[16:17]
	v_lshlrev_b64 v[0:1], 12, v[0:1]
	v_lshl_add_u64 v[0:1], s[26:27], 0, v[0:1]
	v_lshl_add_u64 v[0:1], v[0:1], 0, v[12:13]
	v_lshl_add_u64 v[0:1], v[0:1], 0, v[128:129]
	s_waitcnt lgkmcnt(0)
	global_store_dwordx4 v[0:1], v[4:7], off
	v_add_u32_e32 v0, 0x100, v149
	v_readlane_b32 s22, v253, 45
	v_ashrrev_i32_e32 v4, 3, v0
	v_ashrrev_i32_e32 v5, 31, v4
	v_mad_u64_u32 v[0:1], s[10:11], v4, s13, v[10:11]
	v_lshl_add_u64 v[4:5], v[8:9], 0, v[4:5]
	v_lshlrev_b64 v[4:5], 12, v[4:5]
	ds_read_b128 v[0:3], v0
	v_lshl_add_u64 v[4:5], s[26:27], 0, v[4:5]
	v_lshl_add_u64 v[4:5], v[4:5], 0, v[12:13]
	v_lshl_add_u64 v[14:15], v[4:5], 0, v[128:129]
	v_add_u32_e32 v4, 0x140, v149
	v_ashrrev_i32_e32 v16, 3, v4
	v_mad_u64_u32 v[4:5], s[10:11], v16, s13, v[10:11]
	v_ashrrev_i32_e32 v17, 31, v16
	ds_read_b128 v[4:7], v4
	s_waitcnt lgkmcnt(1)
	global_store_dwordx4 v[14:15], v[0:3], off
	v_readlane_b32 s23, v253, 46
	v_readlane_b32 s24, v253, 47
	v_lshl_add_u64 v[0:1], v[8:9], 0, v[16:17]
	v_lshlrev_b64 v[0:1], 12, v[0:1]
	v_lshl_add_u64 v[0:1], s[26:27], 0, v[0:1]
	v_lshl_add_u64 v[0:1], v[0:1], 0, v[12:13]
	v_lshl_add_u64 v[0:1], v[0:1], 0, v[128:129]
	s_waitcnt lgkmcnt(0)
	global_store_dwordx4 v[0:1], v[4:7], off
	v_add_u32_e32 v0, 0x180, v149
	v_readlane_b32 s25, v253, 48
	v_ashrrev_i32_e32 v4, 3, v0
	v_ashrrev_i32_e32 v5, 31, v4
	v_mad_u64_u32 v[0:1], s[10:11], v4, s13, v[10:11]
	v_lshl_add_u64 v[4:5], v[8:9], 0, v[4:5]
	v_lshlrev_b64 v[4:5], 12, v[4:5]
	ds_read_b128 v[0:3], v0
	v_lshl_add_u64 v[4:5], s[26:27], 0, v[4:5]
	v_lshl_add_u64 v[4:5], v[4:5], 0, v[12:13]
	v_lshl_add_u64 v[14:15], v[4:5], 0, v[128:129]
	v_add_u32_e32 v4, 0x1c0, v149
	v_ashrrev_i32_e32 v16, 3, v4
	v_mad_u64_u32 v[4:5], s[10:11], v16, s13, v[10:11]
	v_ashrrev_i32_e32 v17, 31, v16
	ds_read_b128 v[4:7], v4
	s_waitcnt lgkmcnt(1)
; template <int EPI, int PN>
; __device__ void gemm_phase(const Params& p, const u16* __restrict__ A, const u16* __restrict__ Bt, int nNt, char* smem) {
;     ...
;   for (int q = jb;; q += NJ) {
;     const int pl = q / (4 * PN), w = q % (4 * PN);
;     const int gp = pl * 8 + xcd;
;     if (gp >= npatch) break;
;     ...
;       for (int it = 0; it < 16; ++it) {
;         const int c = it * 64 + laneE, row = c >> 3, seg = c & 7;
;         const uint4 v = *(const uint4*)(et + row * 144 + seg * 16);
;         if (EPI == 0) *(uint4*)(p.proj + (row0 + row) * NPROJ + col0 + seg * 8) = v;
;         else *(uint4*)(p.qp + (row0 + row) * DM + col0 + seg * 8) = v;
;       }
;     }
;     __syncthreads();
;   }
	global_store_dwordx4 v[14:15], v[0:3], off
	v_readlane_b32 s28, v253, 51
	v_readlane_b32 s29, v253, 52
	v_lshl_add_u64 v[0:1], v[8:9], 0, v[16:17]
	v_lshlrev_b64 v[0:1], 12, v[0:1]
	v_lshl_add_u64 v[0:1], s[26:27], 0, v[0:1]
	v_lshl_add_u64 v[0:1], v[0:1], 0, v[12:13]
	v_lshl_add_u64 v[0:1], v[0:1], 0, v[128:129]
	s_waitcnt lgkmcnt(0)
	global_store_dwordx4 v[0:1], v[4:7], off
	v_add_u32_e32 v0, 0x200, v149
	v_readlane_b32 s30, v253, 53
	v_ashrrev_i32_e32 v4, 3, v0
	v_ashrrev_i32_e32 v5, 31, v4
	v_mad_u64_u32 v[0:1], s[10:11], v4, s13, v[10:11]
	v_lshl_add_u64 v[4:5], v[8:9], 0, v[4:5]
	v_lshlrev_b64 v[4:5], 12, v[4:5]
	ds_read_b128 v[0:3], v0
	v_lshl_add_u64 v[4:5], s[26:27], 0, v[4:5]
	v_lshl_add_u64 v[4:5], v[4:5], 0, v[12:13]
	v_lshl_add_u64 v[14:15], v[4:5], 0, v[128:129]
	v_add_u32_e32 v4, 0x240, v149
	v_ashrrev_i32_e32 v16, 3, v4
	v_mad_u64_u32 v[4:5], s[10:11], v16, s13, v[10:11]
	v_ashrrev_i32_e32 v17, 31, v16
	ds_read_b128 v[4:7], v4
	s_waitcnt lgkmcnt(1)
	global_store_dwordx4 v[14:15], v[0:3], off
	v_readlane_b32 s31, v253, 54
	s_nop 0
	v_lshl_add_u64 v[0:1], v[8:9], 0, v[16:17]
	v_lshlrev_b64 v[0:1], 12, v[0:1]
	v_lshl_add_u64 v[0:1], s[26:27], 0, v[0:1]
	v_lshl_add_u64 v[0:1], v[0:1], 0, v[12:13]
	v_lshl_add_u64 v[0:1], v[0:1], 0, v[128:129]
	s_waitcnt lgkmcnt(0)
	global_store_dwordx4 v[0:1], v[4:7], off
	v_add_u32_e32 v0, 0x280, v149
	s_nop 0
	v_ashrrev_i32_e32 v4, 3, v0
	v_ashrrev_i32_e32 v5, 31, v4
	v_mad_u64_u32 v[0:1], s[10:11], v4, s13, v[10:11]
	v_lshl_add_u64 v[4:5], v[8:9], 0, v[4:5]
	v_lshlrev_b64 v[4:5], 12, v[4:5]
	ds_read_b128 v[0:3], v0
	v_lshl_add_u64 v[4:5], s[26:27], 0, v[4:5]
	v_lshl_add_u64 v[4:5], v[4:5], 0, v[12:13]
	v_lshl_add_u64 v[14:15], v[4:5], 0, v[128:129]
	v_add_u32_e32 v4, 0x2c0, v149
	v_ashrrev_i32_e32 v16, 3, v4
	v_mad_u64_u32 v[4:5], s[10:11], v16, s13, v[10:11]
	v_ashrrev_i32_e32 v17, 31, v16
	ds_read_b128 v[4:7], v4
	s_waitcnt lgkmcnt(1)
	global_store_dwordx4 v[14:15], v[0:3], off
	s_nop 1
	v_lshl_add_u64 v[0:1], v[8:9], 0, v[16:17]
	v_lshlrev_b64 v[0:1], 12, v[0:1]
	v_lshl_add_u64 v[0:1], s[26:27], 0, v[0:1]
	v_lshl_add_u64 v[0:1], v[0:1], 0, v[12:13]
	v_lshl_add_u64 v[0:1], v[0:1], 0, v[128:129]
	s_waitcnt lgkmcnt(0)
	global_store_dwordx4 v[0:1], v[4:7], off
	v_add_u32_e32 v0, 0x300, v149
	s_nop 0
	v_ashrrev_i32_e32 v4, 3, v0
	v_ashrrev_i32_e32 v5, 31, v4
	v_mad_u64_u32 v[0:1], s[10:11], v4, s13, v[10:11]
	v_lshl_add_u64 v[4:5], v[8:9], 0, v[4:5]
	v_lshlrev_b64 v[4:5], 12, v[4:5]
	ds_read_b128 v[0:3], v0
	v_lshl_add_u64 v[4:5], s[26:27], 0, v[4:5]
	v_lshl_add_u64 v[4:5], v[4:5], 0, v[12:13]
	v_lshl_add_u64 v[14:15], v[4:5], 0, v[128:129]
	v_add_u32_e32 v4, 0x340, v149
	v_ashrrev_i32_e32 v16, 3, v4
	v_mad_u64_u32 v[4:5], s[10:11], v16, s13, v[10:11]
	v_ashrrev_i32_e32 v17, 31, v16
	ds_read_b128 v[4:7], v4
	s_waitcnt lgkmcnt(1)
	global_store_dwordx4 v[14:15], v[0:3], off
	s_nop 1
	v_lshl_add_u64 v[0:1], v[8:9], 0, v[16:17]
	v_lshlrev_b64 v[0:1], 12, v[0:1]
	v_lshl_add_u64 v[0:1], s[26:27], 0, v[0:1]
	v_lshl_add_u64 v[0:1], v[0:1], 0, v[12:13]
	v_lshl_add_u64 v[0:1], v[0:1], 0, v[128:129]
	s_waitcnt lgkmcnt(0)
	global_store_dwordx4 v[0:1], v[4:7], off
	v_add_u32_e32 v0, 0x380, v149
	s_nop 0
	v_ashrrev_i32_e32 v4, 3, v0
	v_ashrrev_i32_e32 v5, 31, v4
	v_mad_u64_u32 v[0:1], s[10:11], v4, s13, v[10:11]
	v_lshl_add_u64 v[4:5], v[8:9], 0, v[4:5]
	v_lshlrev_b64 v[4:5], 12, v[4:5]
	v_lshl_add_u64 v[4:5], s[26:27], 0, v[4:5]
	v_lshl_add_u64 v[4:5], v[4:5], 0, v[12:13]
	v_lshl_add_u64 v[14:15], v[4:5], 0, v[128:129]
	v_add_u32_e32 v4, 0x3c0, v149
	v_ashrrev_i32_e32 v16, 3, v4
	ds_read_b128 v[0:3], v0
	v_mad_u64_u32 v[4:5], s[10:11], v16, s13, v[10:11]
	v_readlane_b32 s10, v254, 28
	s_add_i32 s34, s34, s10
	s_ashr_i32 s10, s34, 31
	v_ashrrev_i32_e32 v17, 31, v16
	s_lshr_b32 s10, s10, 27
	ds_read_b128 v[4:7], v4
	s_waitcnt lgkmcnt(1)
	global_store_dwordx4 v[14:15], v[0:3], off
	s_add_i32 s10, s34, s10
	s_ashr_i32 s10, s10, 5
	v_lshl_add_u64 v[0:1], v[8:9], 0, v[16:17]
	v_lshlrev_b64 v[0:1], 12, v[0:1]
	v_lshl_add_u64 v[0:1], s[26:27], 0, v[0:1]
	s_lshl_b32 s10, s10, 3
	v_readlane_b32 s11, v254, 24
	v_lshl_add_u64 v[0:1], v[0:1], 0, v[12:13]
	s_or_b32 s11, s10, s11
	v_lshl_add_u64 v[0:1], v[0:1], 0, v[128:129]
	s_cmp_gt_i32 s11, 31
	s_waitcnt lgkmcnt(0)
	global_store_dwordx4 v[0:1], v[4:7], off
	s_waitcnt vmcnt(63) expcnt(7) lgkmcnt(15)
	s_barrier
	s_cbranch_scc0 .LBB0_722
